# v16 + all s_setprio toggles of the GEMM K-loops removed (priority measured irrelevant; 4 fewer issue slots per 32-MFMA block)
# speedup vs baseline: 1.0109x; 1.0033x over previous
; #define PG8_STAGE(bufoff, gbase, voff) do { _Pragma("unroll") for (int _i = 0; _i < 2; ++_i) \
;         __builtin_amdgcn_global_load_lds((const unsigned*)((const char*)(gbase) + (voff)[_i]), (PG8_LAS unsigned*)(lds + (bufoff) + ldsw + _i * 8192), 16, 0, 0); } while (0)
; #define PG8_LDA(dst, b, h) do { _Pragma("unroll") for (int m = 0; m < 4; ++m) _Pragma("unroll") for (int k = 0; k < 2; ++k) dst[m][k] = *(const PG8_LAS bf16x8*)(lds + PG8_SA(b, h) + aoff + m * 2048 + k * 1024); } while (0)
; #define PG8_LDB(dst, b, h) do { _Pragma("unroll") for (int n = 0; n < 2; ++n) _Pragma("unroll") for (int k = 0; k < 2; ++k) dst[n][k] = *(const PG8_LAS bf16x8*)(lds + PG8_SB(b, h) + boff + n * 2048 + k * 1024); } while (0)
; #define PG8_MMA(ai, bj, At, Bt) do { __builtin_amdgcn_s_setprio(1); _Pragma("unroll") for (int m = 0; m < 4; ++m) _Pragma("unroll") for (int n = 0; n < 2; ++n) _Pragma("unroll") for (int k = 0; k < 2; ++k) \
;         acc[ai][bj][m][n] = __builtin_amdgcn_mfma_f32_16x16x32_bf16(Bt[n][k], At[m][k], acc[ai][bj][m][n], 0, 0, 0); __builtin_amdgcn_s_setprio(0); } while (0)
; #define PG8_WAIT_V(n) asm volatile("s_waitcnt vmcnt(" #n ")" ::: "memory")
; #define PG8_WAIT_L(n) asm volatile("s_waitcnt lgkmcnt(" #n ")" ::: "memory")
; #define PG8_BAR __builtin_amdgcn_s_barrier()
; #define PG8_SCHED __builtin_amdgcn_sched_barrier(0)
; template <class Epi, class Sched, bool ALIGN_EPI = false, bool SP2 = false>
; __device__ __forceinline__ void gemm_phase(PG8_LAS unsigned char* lds, const Gemm g, const Sched& S, const Epi& E) {
;     ...
;             PG8_LDB(B0, 0, 0); PG8_LDB(B1, 0, 1); PG8_SCHED; PG8_LDA(At, 0, 0); PG8_STAGE(PG8_SA(1, 1), a1 + hstep, voffA);
;             PG8_WAIT_V(8); PG8_WAIT_L(0); PG8_BAR; PG8_MMA(0, 0, At, B0); PG8_MMA(0, 1, At, B1); PG8_BAR; PG8_SCHED;
;             PG8_LDA(At, 0, 1); PG8_STAGE(PG8_SB(0, 0), b2, voffB); PG8_STAGE(PG8_SB(0, 1), b2 + hstepB, voffB); PG8_STAGE(PG8_SA(0, 0), a2, voffA);
.LBB0_192:
	ds_read_b128 v[146:149], v152
	ds_read_b128 v[156:159], v152 offset:1024
	ds_read_b128 v[160:163], v152 offset:2048
	ds_read_b128 v[164:167], v152 offset:3072
	ds_read_b128 v[168:171], v153
	ds_read_b128 v[172:175], v153 offset:1024
	ds_read_b128 v[176:179], v153 offset:2048
	ds_read_b128 v[180:183], v153 offset:3072
	s_add_u32 s22, s20, 0xfffc0080
	s_addc_u32 s23, s21, -1
	s_cmp_eq_u32 s75, 12
	s_cselect_b32 s25, s5, s23
	s_cselect_b32 s24, s13, s22
	s_cselect_b32 s23, s11, s74
	s_cselect_b32 s22, s19, s73
	v_lshl_add_u64 v[216:217], s[20:21], 0, v[138:139]
	s_add_i32 m0, s27, 0xc000
	ds_read_b128 v[184:187], v154
	ds_read_b128 v[188:191], v154 offset:1024
	ds_read_b128 v[192:195], v154 offset:2048
	ds_read_b128 v[196:199], v154 offset:3072
	ds_read_b128 v[200:203], v154 offset:4096
	ds_read_b128 v[204:207], v154 offset:5120
	ds_read_b128 v[208:211], v154 offset:6144
	ds_read_b128 v[212:215], v154 offset:7168
	global_load_lds_dwordx4 v[216:217], off
	v_lshl_add_u64 v[216:217], s[20:21], 0, v[140:141]
	s_add_i32 m0, s27, 0xe000
	s_nop 0
	global_load_lds_dwordx4 v[216:217], off
	s_waitcnt vmcnt(8)
	s_waitcnt lgkmcnt(0)
	s_barrier
	s_waitcnt lgkmcnt(0)
	v_mfma_f32_16x16x32_bf16 v[126:129], v[146:149], v[184:187], v[126:129]
	v_mfma_f32_16x16x32_bf16 v[122:125], v[160:163], v[184:187], v[122:125]
	v_mfma_f32_16x16x32_bf16 v[114:117], v[146:149], v[192:195], v[114:117]
	v_mfma_f32_16x16x32_bf16 v[106:109], v[160:163], v[192:195], v[106:109]
	v_mfma_f32_16x16x32_bf16 v[98:101], v[146:149], v[200:203], v[98:101]
	v_mfma_f32_16x16x32_bf16 v[90:93], v[160:163], v[200:203], v[90:93]
	v_mfma_f32_16x16x32_bf16 v[82:85], v[146:149], v[208:211], v[82:85]
	v_mfma_f32_16x16x32_bf16 v[74:77], v[160:163], v[208:211], v[74:77]
	v_mfma_f32_16x16x32_bf16 v[126:129], v[156:159], v[188:191], v[126:129]
	v_mfma_f32_16x16x32_bf16 v[122:125], v[164:167], v[188:191], v[122:125]
	v_mfma_f32_16x16x32_bf16 v[114:117], v[156:159], v[196:199], v[114:117]
	v_mfma_f32_16x16x32_bf16 v[106:109], v[164:167], v[196:199], v[106:109]
	v_mfma_f32_16x16x32_bf16 v[98:101], v[156:159], v[204:207], v[98:101]
	v_mfma_f32_16x16x32_bf16 v[90:93], v[164:167], v[204:207], v[90:93]
	v_mfma_f32_16x16x32_bf16 v[82:85], v[156:159], v[212:215], v[82:85]
	v_mfma_f32_16x16x32_bf16 v[74:77], v[164:167], v[212:215], v[74:77]
	v_mfma_f32_16x16x32_bf16 v[118:121], v[168:171], v[184:187], v[118:121]
	v_mfma_f32_16x16x32_bf16 v[110:113], v[176:179], v[184:187], v[110:113]
	v_mfma_f32_16x16x32_bf16 v[102:105], v[168:171], v[192:195], v[102:105]
	v_mfma_f32_16x16x32_bf16 v[94:97], v[176:179], v[192:195], v[94:97]
	v_mfma_f32_16x16x32_bf16 v[86:89], v[168:171], v[200:203], v[86:89]
	v_mfma_f32_16x16x32_bf16 v[78:81], v[176:179], v[200:203], v[78:81]
	v_mfma_f32_16x16x32_bf16 v[70:73], v[168:171], v[208:211], v[70:73]
	v_mfma_f32_16x16x32_bf16 v[66:69], v[176:179], v[208:211], v[66:69]
	v_mfma_f32_16x16x32_bf16 v[118:121], v[172:175], v[188:191], v[118:121]
	v_mfma_f32_16x16x32_bf16 v[110:113], v[180:183], v[188:191], v[110:113]
	v_mfma_f32_16x16x32_bf16 v[102:105], v[172:175], v[196:199], v[102:105]
	v_mfma_f32_16x16x32_bf16 v[94:97], v[180:183], v[196:199], v[94:97]
	v_mfma_f32_16x16x32_bf16 v[86:89], v[172:175], v[204:207], v[86:89]
	v_mfma_f32_16x16x32_bf16 v[78:81], v[180:183], v[204:207], v[78:81]
	v_mfma_f32_16x16x32_bf16 v[70:73], v[172:175], v[212:215], v[70:73]
	v_mfma_f32_16x16x32_bf16 v[66:69], v[180:183], v[212:215], v[66:69]
	s_barrier
	s_add_i32 s76, s69, s26
	v_lshl_add_u64 v[216:217], s[22:23], 0, v[132:133]
	s_mov_b32 m0, s76
	ds_read_b128 v[184:187], v154 offset:16384
	ds_read_b128 v[188:191], v154 offset:17408
	ds_read_b128 v[192:195], v154 offset:18432
	ds_read_b128 v[196:199], v154 offset:19456
	ds_read_b128 v[200:203], v154 offset:20480
	ds_read_b128 v[204:207], v154 offset:21504
	ds_read_b128 v[208:211], v154 offset:22528
	ds_read_b128 v[212:215], v154 offset:23552
	global_load_lds_dwordx4 v[216:217], off
	s_add_i32 m0, s76, 0x2000
	s_add_u32 s76, s22, 0x10000
	v_lshl_add_u64 v[218:219], s[22:23], 0, v[136:137]
	s_addc_u32 s77, s23, 0
	s_add_i32 s78, s70, s26
	global_load_lds_dwordx4 v[218:219], off
	v_lshl_add_u64 v[220:221], s[76:77], 0, v[132:133]
	s_mov_b32 m0, s78
	v_lshl_add_u64 v[222:223], s[24:25], 0, v[134:135]
	global_load_lds_dwordx4 v[220:221], off
	v_lshl_add_u64 v[220:221], s[76:77], 0, v[136:137]
	s_add_i32 m0, s78, 0x2000
	s_nop 0
	global_load_lds_dwordx4 v[220:221], off
	v_lshl_add_u64 v[220:221], s[24:25], 0, v[130:131]
	s_mov_b32 m0, s27
	s_nop 0
	global_load_lds_dwordx4 v[220:221], off
	s_mov_b32 m0, s28
	s_nop 0
	global_load_lds_dwordx4 v[222:223], off
	s_waitcnt vmcnt(8)
	s_waitcnt lgkmcnt(0)
	s_barrier
; #define PG8_STAGE(bufoff, gbase, voff) do { _Pragma("unroll") for (int _i = 0; _i < 2; ++_i) \
;         __builtin_amdgcn_global_load_lds((const unsigned*)((const char*)(gbase) + (voff)[_i]), (PG8_LAS unsigned*)(lds + (bufoff) + ldsw + _i * 8192), 16, 0, 0); } while (0)
; #define PG8_LDA(dst, b, h) do { _Pragma("unroll") for (int m = 0; m < 4; ++m) _Pragma("unroll") for (int k = 0; k < 2; ++k) dst[m][k] = *(const PG8_LAS bf16x8*)(lds + PG8_SA(b, h) + aoff + m * 2048 + k * 1024); } while (0)
; #define PG8_LDB(dst, b, h) do { _Pragma("unroll") for (int n = 0; n < 2; ++n) _Pragma("unroll") for (int k = 0; k < 2; ++k) dst[n][k] = *(const PG8_LAS bf16x8*)(lds + PG8_SB(b, h) + boff + n * 2048 + k * 1024); } while (0)
; #define PG8_MMA(ai, bj, At, Bt) do { __builtin_amdgcn_s_setprio(1); _Pragma("unroll") for (int m = 0; m < 4; ++m) _Pragma("unroll") for (int n = 0; n < 2; ++n) _Pragma("unroll") for (int k = 0; k < 2; ++k) \
;         acc[ai][bj][m][n] = __builtin_amdgcn_mfma_f32_16x16x32_bf16(Bt[n][k], At[m][k], acc[ai][bj][m][n], 0, 0, 0); __builtin_amdgcn_s_setprio(0); } while (0)
; #define PG8_WAIT_V(n) asm volatile("s_waitcnt vmcnt(" #n ")" ::: "memory")
; #define PG8_WAIT_L(n) asm volatile("s_waitcnt lgkmcnt(" #n ")" ::: "memory")
; #define PG8_BAR __builtin_amdgcn_s_barrier()
; #define PG8_SCHED __builtin_amdgcn_sched_barrier(0)
; template <class Epi, class Sched, bool ALIGN_EPI = false, bool SP2 = false>
; __device__ __forceinline__ void gemm_phase(PG8_LAS unsigned char* lds, const Gemm g, const Sched& S, const Epi& E) {
;     ...
;             PG8_WAIT_V(8); PG8_WAIT_L(0); PG8_BAR; PG8_MMA(1, 0, At, B0); PG8_MMA(1, 1, At, B1); PG8_BAR; PG8_SCHED;
;             PG8_LDB(B0, 1, 0); PG8_LDB(B1, 1, 1); PG8_SCHED; PG8_LDA(At, 1, 0); PG8_STAGE(PG8_SA(0, 1), a2 + hstep, voffA);
;             PG8_WAIT_V(8); PG8_WAIT_L(0); PG8_BAR; PG8_MMA(0, 0, At, B0); PG8_MMA(0, 1, At, B1); PG8_BAR; PG8_SCHED;
	s_waitcnt lgkmcnt(0)
	v_mfma_f32_16x16x32_bf16 v[62:65], v[146:149], v[184:187], v[62:65]
	v_mfma_f32_16x16x32_bf16 v[58:61], v[160:163], v[184:187], v[58:61]
	v_mfma_f32_16x16x32_bf16 v[50:53], v[146:149], v[192:195], v[50:53]
	v_mfma_f32_16x16x32_bf16 v[42:45], v[160:163], v[192:195], v[42:45]
	v_mfma_f32_16x16x32_bf16 v[34:37], v[146:149], v[200:203], v[34:37]
	v_mfma_f32_16x16x32_bf16 v[26:29], v[160:163], v[200:203], v[26:29]
	v_mfma_f32_16x16x32_bf16 v[18:21], v[146:149], v[208:211], v[18:21]
	v_mfma_f32_16x16x32_bf16 v[10:13], v[160:163], v[208:211], v[10:13]
	v_mfma_f32_16x16x32_bf16 v[62:65], v[156:159], v[188:191], v[62:65]
	v_mfma_f32_16x16x32_bf16 v[58:61], v[164:167], v[188:191], v[58:61]
	v_mfma_f32_16x16x32_bf16 v[50:53], v[156:159], v[196:199], v[50:53]
	v_mfma_f32_16x16x32_bf16 v[42:45], v[164:167], v[196:199], v[42:45]
	v_mfma_f32_16x16x32_bf16 v[34:37], v[156:159], v[204:207], v[34:37]
	v_mfma_f32_16x16x32_bf16 v[26:29], v[164:167], v[204:207], v[26:29]
	v_mfma_f32_16x16x32_bf16 v[18:21], v[156:159], v[212:215], v[18:21]
	v_mfma_f32_16x16x32_bf16 v[10:13], v[164:167], v[212:215], v[10:13]
	v_mfma_f32_16x16x32_bf16 v[54:57], v[168:171], v[184:187], v[54:57]
	v_mfma_f32_16x16x32_bf16 v[46:49], v[176:179], v[184:187], v[46:49]
	v_mfma_f32_16x16x32_bf16 v[38:41], v[168:171], v[192:195], v[38:41]
	v_mfma_f32_16x16x32_bf16 v[30:33], v[176:179], v[192:195], v[30:33]
	v_mfma_f32_16x16x32_bf16 v[22:25], v[168:171], v[200:203], v[22:25]
	v_mfma_f32_16x16x32_bf16 v[14:17], v[176:179], v[200:203], v[14:17]
	v_mfma_f32_16x16x32_bf16 v[6:9], v[168:171], v[208:211], v[6:9]
	v_mfma_f32_16x16x32_bf16 v[2:5], v[176:179], v[208:211], v[2:5]
	v_mfma_f32_16x16x32_bf16 v[54:57], v[172:175], v[188:191], v[54:57]
	v_mfma_f32_16x16x32_bf16 v[46:49], v[180:183], v[188:191], v[46:49]
	v_mfma_f32_16x16x32_bf16 v[38:41], v[172:175], v[196:199], v[38:41]
	v_mfma_f32_16x16x32_bf16 v[30:33], v[180:183], v[196:199], v[30:33]
	v_mfma_f32_16x16x32_bf16 v[22:25], v[172:175], v[204:207], v[22:25]
	v_mfma_f32_16x16x32_bf16 v[14:17], v[180:183], v[204:207], v[14:17]
	v_mfma_f32_16x16x32_bf16 v[6:9], v[172:175], v[212:215], v[6:9]
	v_mfma_f32_16x16x32_bf16 v[2:5], v[180:183], v[212:215], v[2:5]
	s_barrier
	s_add_i32 s76, 0, 0x18000
	v_add_u32_e32 v155, s76, v150
	s_add_i32 s77, 0, 0x1c000
	ds_read_b128 v[146:149], v155
	ds_read_b128 v[156:159], v155 offset:1024
	ds_read_b128 v[160:163], v155 offset:2048
	ds_read_b128 v[164:167], v155 offset:3072
	v_add_u32_e32 v155, s77, v150
	ds_read_b128 v[168:171], v155
	ds_read_b128 v[172:175], v155 offset:1024
	ds_read_b128 v[176:179], v155 offset:2048
	ds_read_b128 v[180:183], v155 offset:3072
	s_add_u32 s24, s24, 0x40000
	s_addc_u32 s25, s25, 0
	s_mov_b32 m0, s29
	v_lshl_add_u64 v[224:225], s[24:25], 0, v[130:131]
	ds_read_b128 v[184:187], v154 offset:32768
	ds_read_b128 v[188:191], v154 offset:33792
	ds_read_b128 v[192:195], v154 offset:34816
	ds_read_b128 v[196:199], v154 offset:35840
	ds_read_b128 v[200:203], v154 offset:36864
	ds_read_b128 v[204:207], v154 offset:37888
	ds_read_b128 v[208:211], v154 offset:38912
	ds_read_b128 v[212:215], v154 offset:39936
	global_load_lds_dwordx4 v[224:225], off
	v_lshl_add_u64 v[224:225], s[24:25], 0, v[134:135]
	s_mov_b32 m0, s30
	s_nop 0
	global_load_lds_dwordx4 v[224:225], off
	s_waitcnt vmcnt(8)
	s_waitcnt lgkmcnt(0)
	s_barrier
	s_waitcnt lgkmcnt(0)
	v_mfma_f32_16x16x32_bf16 v[126:129], v[146:149], v[184:187], v[126:129]
	v_mfma_f32_16x16x32_bf16 v[122:125], v[160:163], v[184:187], v[122:125]
	v_mfma_f32_16x16x32_bf16 v[114:117], v[146:149], v[192:195], v[114:117]
	v_mfma_f32_16x16x32_bf16 v[106:109], v[160:163], v[192:195], v[106:109]
	v_mfma_f32_16x16x32_bf16 v[98:101], v[146:149], v[200:203], v[98:101]
	v_mfma_f32_16x16x32_bf16 v[90:93], v[160:163], v[200:203], v[90:93]
	v_mfma_f32_16x16x32_bf16 v[82:85], v[146:149], v[208:211], v[82:85]
	v_mfma_f32_16x16x32_bf16 v[74:77], v[160:163], v[208:211], v[74:77]
	v_mfma_f32_16x16x32_bf16 v[126:129], v[156:159], v[188:191], v[126:129]
	v_mfma_f32_16x16x32_bf16 v[122:125], v[164:167], v[188:191], v[122:125]
	v_mfma_f32_16x16x32_bf16 v[114:117], v[156:159], v[196:199], v[114:117]
	v_mfma_f32_16x16x32_bf16 v[106:109], v[164:167], v[196:199], v[106:109]
	v_mfma_f32_16x16x32_bf16 v[98:101], v[156:159], v[204:207], v[98:101]
	v_mfma_f32_16x16x32_bf16 v[90:93], v[164:167], v[204:207], v[90:93]
	v_mfma_f32_16x16x32_bf16 v[82:85], v[156:159], v[212:215], v[82:85]
	v_mfma_f32_16x16x32_bf16 v[74:77], v[164:167], v[212:215], v[74:77]
	v_mfma_f32_16x16x32_bf16 v[118:121], v[168:171], v[184:187], v[118:121]
	v_mfma_f32_16x16x32_bf16 v[110:113], v[176:179], v[184:187], v[110:113]
	v_mfma_f32_16x16x32_bf16 v[102:105], v[168:171], v[192:195], v[102:105]
	v_mfma_f32_16x16x32_bf16 v[94:97], v[176:179], v[192:195], v[94:97]
	v_mfma_f32_16x16x32_bf16 v[86:89], v[168:171], v[200:203], v[86:89]
	v_mfma_f32_16x16x32_bf16 v[78:81], v[176:179], v[200:203], v[78:81]
	v_mfma_f32_16x16x32_bf16 v[70:73], v[168:171], v[208:211], v[70:73]
	v_mfma_f32_16x16x32_bf16 v[66:69], v[176:179], v[208:211], v[66:69]
	v_mfma_f32_16x16x32_bf16 v[118:121], v[172:175], v[188:191], v[118:121]
	v_mfma_f32_16x16x32_bf16 v[110:113], v[180:183], v[188:191], v[110:113]
	v_mfma_f32_16x16x32_bf16 v[102:105], v[172:175], v[196:199], v[102:105]
	v_mfma_f32_16x16x32_bf16 v[94:97], v[180:183], v[196:199], v[94:97]
	v_mfma_f32_16x16x32_bf16 v[86:89], v[172:175], v[204:207], v[86:89]
	v_mfma_f32_16x16x32_bf16 v[78:81], v[180:183], v[204:207], v[78:81]
	v_mfma_f32_16x16x32_bf16 v[70:73], v[172:175], v[212:215], v[70:73]
	v_mfma_f32_16x16x32_bf16 v[66:69], v[180:183], v[212:215], v[66:69]
	s_barrier
; #define PG8_STAGE(bufoff, gbase, voff) do { _Pragma("unroll") for (int _i = 0; _i < 2; ++_i) \
;         __builtin_amdgcn_global_load_lds((const unsigned*)((const char*)(gbase) + (voff)[_i]), (PG8_LAS unsigned*)(lds + (bufoff) + ldsw + _i * 8192), 16, 0, 0); } while (0)
; #define PG8_LDA(dst, b, h) do { _Pragma("unroll") for (int m = 0; m < 4; ++m) _Pragma("unroll") for (int k = 0; k < 2; ++k) dst[m][k] = *(const PG8_LAS bf16x8*)(lds + PG8_SA(b, h) + aoff + m * 2048 + k * 1024); } while (0)
; #define PG8_MMA(ai, bj, At, Bt) do { __builtin_amdgcn_s_setprio(1); _Pragma("unroll") for (int m = 0; m < 4; ++m) _Pragma("unroll") for (int n = 0; n < 2; ++n) _Pragma("unroll") for (int k = 0; k < 2; ++k) \
;         acc[ai][bj][m][n] = __builtin_amdgcn_mfma_f32_16x16x32_bf16(Bt[n][k], At[m][k], acc[ai][bj][m][n], 0, 0, 0); __builtin_amdgcn_s_setprio(0); } while (0)
; #define PG8_WAIT_V(n) asm volatile("s_waitcnt vmcnt(" #n ")" ::: "memory")
; #define PG8_WAIT_L(n) asm volatile("s_waitcnt lgkmcnt(" #n ")" ::: "memory")
; #define PG8_BAR __builtin_amdgcn_s_barrier()
; #define PG8_SCHED __builtin_amdgcn_sched_barrier(0)
; template <class Epi, class Sched, bool ALIGN_EPI = false, bool SP2 = false>
; __device__ __forceinline__ void gemm_phase(PG8_LAS unsigned char* lds, const Gemm g, const Sched& S, const Epi& E) {
;     ...
;             PG8_LDA(At, 1, 1); PG8_STAGE(PG8_SB(1, 0), b3, voffB); PG8_STAGE(PG8_SB(1, 1), b3 + hstepB, voffB); PG8_STAGE(PG8_SA(1, 0), a3, voffA);
;             PG8_WAIT_V(8); PG8_WAIT_L(0); PG8_BAR; PG8_MMA(1, 0, At, B0); PG8_MMA(1, 1, At, B1); PG8_BAR; PG8_SCHED;
;     ...
;         if constexpr (ALIGN_EPI) { if (wr == 0) PG8_BAR; }
	s_add_i32 s24, s76, s26
	v_lshl_add_u64 v[216:217], v[216:217], 0, s[6:7]
	s_mov_b32 m0, s24
	ds_read_b128 v[184:187], v154 offset:49152
	ds_read_b128 v[188:191], v154 offset:50176
	ds_read_b128 v[192:195], v154 offset:51200
	ds_read_b128 v[196:199], v154 offset:52224
	ds_read_b128 v[200:203], v154 offset:53248
	ds_read_b128 v[204:207], v154 offset:54272
	ds_read_b128 v[208:211], v154 offset:55296
	ds_read_b128 v[212:215], v154 offset:56320
	global_load_lds_dwordx4 v[216:217], off
	s_add_i32 m0, s24, 0x2000
	s_add_u32 s22, s22, 0x10080
	v_lshl_add_u64 v[216:217], v[218:219], 0, s[6:7]
	s_addc_u32 s23, s23, 0
	s_add_i32 s24, s77, s26
	global_load_lds_dwordx4 v[216:217], off
	v_lshl_add_u64 v[216:217], s[22:23], 0, v[132:133]
	s_mov_b32 m0, s24
	s_nop 0
	global_load_lds_dwordx4 v[216:217], off
	v_lshl_add_u64 v[216:217], s[22:23], 0, v[136:137]
	s_add_i32 m0, s24, 0x2000
	s_nop 0
	global_load_lds_dwordx4 v[216:217], off
	v_lshl_add_u64 v[216:217], v[220:221], 0, s[6:7]
	s_mov_b32 m0, s33
	s_nop 0
	global_load_lds_dwordx4 v[216:217], off
	v_lshl_add_u64 v[216:217], v[222:223], 0, s[6:7]
	s_mov_b32 m0, s34
	s_nop 0
	global_load_lds_dwordx4 v[216:217], off
	s_waitcnt vmcnt(8)
	s_waitcnt lgkmcnt(0)
	s_barrier
	s_waitcnt lgkmcnt(0)
	v_mfma_f32_16x16x32_bf16 v[62:65], v[146:149], v[184:187], v[62:65]
	v_mfma_f32_16x16x32_bf16 v[58:61], v[160:163], v[184:187], v[58:61]
	v_mfma_f32_16x16x32_bf16 v[50:53], v[146:149], v[192:195], v[50:53]
	v_mfma_f32_16x16x32_bf16 v[42:45], v[160:163], v[192:195], v[42:45]
	v_mfma_f32_16x16x32_bf16 v[34:37], v[146:149], v[200:203], v[34:37]
	v_mfma_f32_16x16x32_bf16 v[26:29], v[160:163], v[200:203], v[26:29]
	v_mfma_f32_16x16x32_bf16 v[18:21], v[146:149], v[208:211], v[18:21]
	v_mfma_f32_16x16x32_bf16 v[10:13], v[160:163], v[208:211], v[10:13]
	v_mfma_f32_16x16x32_bf16 v[62:65], v[156:159], v[188:191], v[62:65]
	v_mfma_f32_16x16x32_bf16 v[58:61], v[164:167], v[188:191], v[58:61]
	v_mfma_f32_16x16x32_bf16 v[50:53], v[156:159], v[196:199], v[50:53]
	v_mfma_f32_16x16x32_bf16 v[42:45], v[164:167], v[196:199], v[42:45]
	v_mfma_f32_16x16x32_bf16 v[34:37], v[156:159], v[204:207], v[34:37]
	v_mfma_f32_16x16x32_bf16 v[26:29], v[164:167], v[204:207], v[26:29]
	v_mfma_f32_16x16x32_bf16 v[18:21], v[156:159], v[212:215], v[18:21]
	v_mfma_f32_16x16x32_bf16 v[10:13], v[164:167], v[212:215], v[10:13]
	v_mfma_f32_16x16x32_bf16 v[54:57], v[168:171], v[184:187], v[54:57]
	v_mfma_f32_16x16x32_bf16 v[46:49], v[176:179], v[184:187], v[46:49]
	v_mfma_f32_16x16x32_bf16 v[38:41], v[168:171], v[192:195], v[38:41]
	v_mfma_f32_16x16x32_bf16 v[30:33], v[176:179], v[192:195], v[30:33]
	v_mfma_f32_16x16x32_bf16 v[22:25], v[168:171], v[200:203], v[22:25]
	v_mfma_f32_16x16x32_bf16 v[14:17], v[176:179], v[200:203], v[14:17]
	v_mfma_f32_16x16x32_bf16 v[6:9], v[168:171], v[208:211], v[6:9]
	v_mfma_f32_16x16x32_bf16 v[2:5], v[176:179], v[208:211], v[2:5]
	v_mfma_f32_16x16x32_bf16 v[54:57], v[172:175], v[188:191], v[54:57]
	v_mfma_f32_16x16x32_bf16 v[46:49], v[180:183], v[188:191], v[46:49]
	v_mfma_f32_16x16x32_bf16 v[38:41], v[172:175], v[196:199], v[38:41]
	v_mfma_f32_16x16x32_bf16 v[30:33], v[180:183], v[196:199], v[30:33]
	v_mfma_f32_16x16x32_bf16 v[22:25], v[172:175], v[204:207], v[22:25]
	v_mfma_f32_16x16x32_bf16 v[14:17], v[180:183], v[204:207], v[14:17]
	v_mfma_f32_16x16x32_bf16 v[6:9], v[172:175], v[212:215], v[6:9]
	v_mfma_f32_16x16x32_bf16 v[2:5], v[180:183], v[212:215], v[2:5]
	s_barrier
	s_add_i32 s75, s75, 2
	s_add_u32 s20, s20, 0x100
	s_addc_u32 s21, s21, 0
	s_add_u32 s73, s73, 0x100
	s_addc_u32 s74, s74, 0
	s_cmp_gt_u32 s75, 13
	s_cbranch_scc0 .LBB0_192
	s_and_b64 vcc, exec, s[8:9]
	s_cbranch_vccz .LBB0_195
	s_barrier

; #define PG8_STAGE(bufoff, gbase, voff) do { _Pragma("unroll") for (int _i = 0; _i < 2; ++_i) \
;         __builtin_amdgcn_global_load_lds((const unsigned*)((const char*)(gbase) + (voff)[_i]), (PG8_LAS unsigned*)(lds + (bufoff) + ldsw + _i * 8192), 16, 0, 0); } while (0)
; #define PG8_LDA(dst, b, h) do { _Pragma("unroll") for (int m = 0; m < 4; ++m) _Pragma("unroll") for (int k = 0; k < 2; ++k) dst[m][k] = *(const PG8_LAS bf16x8*)(lds + PG8_SA(b, h) + aoff + m * 2048 + k * 1024); } while (0)
; #define PG8_LDB(dst, b, h) do { _Pragma("unroll") for (int n = 0; n < 2; ++n) _Pragma("unroll") for (int k = 0; k < 2; ++k) dst[n][k] = *(const PG8_LAS bf16x8*)(lds + PG8_SB(b, h) + boff + n * 2048 + k * 1024); } while (0)
; #define PG8_MMA(ai, bj, At, Bt) do { __builtin_amdgcn_s_setprio(1); _Pragma("unroll") for (int m = 0; m < 4; ++m) _Pragma("unroll") for (int n = 0; n < 2; ++n) _Pragma("unroll") for (int k = 0; k < 2; ++k) \
;         acc[ai][bj][m][n] = __builtin_amdgcn_mfma_f32_16x16x32_bf16(Bt[n][k], At[m][k], acc[ai][bj][m][n], 0, 0, 0); __builtin_amdgcn_s_setprio(0); } while (0)
; #define PG8_WAIT_V(n) asm volatile("s_waitcnt vmcnt(" #n ")" ::: "memory")
; #define PG8_WAIT_L(n) asm volatile("s_waitcnt lgkmcnt(" #n ")" ::: "memory")
; #define PG8_BAR __builtin_amdgcn_s_barrier()
; #define PG8_SCHED __builtin_amdgcn_sched_barrier(0)
; template <class Epi, class Sched, bool ALIGN_EPI = false, bool SP2 = false>
; __device__ __forceinline__ void gemm_phase(PG8_LAS unsigned char* lds, const Gemm g, const Sched& S, const Epi& E) {
;     ...
;             PG8_LDB(B0, 0, 0); PG8_LDB(B1, 0, 1); PG8_SCHED; PG8_LDA(At, 0, 0); PG8_STAGE(PG8_SA(1, 1), a1 + hstep, voffA);
;             PG8_WAIT_V(8); PG8_WAIT_L(0); PG8_BAR; PG8_MMA(0, 0, At, B0); PG8_MMA(0, 1, At, B1); PG8_BAR; PG8_SCHED;
;             PG8_LDA(At, 0, 1); PG8_STAGE(PG8_SB(0, 0), b2, voffB); PG8_STAGE(PG8_SB(0, 1), b2 + hstepB, voffB); PG8_STAGE(PG8_SA(0, 0), a2, voffA);
.LBB0_1094:
	v_add_u32_e32 v3, s46, v224
	ds_read_b128 v[134:137], v3
	ds_read_b128 v[138:141], v3 offset:1024
	ds_read_b128 v[142:145], v3 offset:2048
	ds_read_b128 v[146:149], v3 offset:3072
	v_add_u32_e32 v3, s47, v224
	s_add_u32 s26, s22, s24
	ds_read_b128 v[150:153], v3
	ds_read_b128 v[154:157], v3 offset:1024
	ds_read_b128 v[158:161], v3 offset:2048
	ds_read_b128 v[162:165], v3 offset:3072
	s_addc_u32 s27, s23, s25
	s_add_u32 s26, s26, 0x100
	s_addc_u32 s27, s27, 0
	s_add_u32 s58, s62, s24
	s_addc_u32 s59, s63, s25
	s_cmpk_eq_i32 s24, 0x700
	s_cselect_b32 s29, s17, s27
	s_cselect_b32 s28, s54, s26
	s_cselect_b32 s27, s56, s59
	s_cselect_b32 s26, s57, s58
	v_lshl_add_u64 v[4:5], v[214:215], 0, s[24:25]
	s_add_i32 m0, s33, 0xc000
	ds_read_b128 v[166:169], v226
	ds_read_b128 v[170:173], v226 offset:1024
	ds_read_b128 v[174:177], v226 offset:2048
	ds_read_b128 v[178:181], v226 offset:3072
	ds_read_b128 v[182:185], v226 offset:4096
	ds_read_b128 v[186:189], v226 offset:5120
	ds_read_b128 v[190:193], v226 offset:6144
	ds_read_b128 v[194:197], v226 offset:7168
	global_load_lds_dwordx4 v[4:5], off
	v_lshl_add_u64 v[4:5], v[216:217], 0, s[24:25]
	s_add_i32 m0, s33, 0xe000
	s_nop 0
	global_load_lds_dwordx4 v[4:5], off
	s_waitcnt vmcnt(8)
	s_waitcnt lgkmcnt(0)
	s_barrier
	s_waitcnt lgkmcnt(0)
	v_mfma_f32_16x16x32_bf16 v[130:133], v[134:137], v[166:169], v[130:133]
	v_mfma_f32_16x16x32_bf16 v[126:129], v[142:145], v[166:169], v[126:129]
	v_mfma_f32_16x16x32_bf16 v[114:117], v[134:137], v[174:177], v[114:117]
	v_mfma_f32_16x16x32_bf16 v[110:113], v[142:145], v[174:177], v[110:113]
	v_mfma_f32_16x16x32_bf16 v[98:101], v[134:137], v[182:185], v[98:101]
	v_mfma_f32_16x16x32_bf16 v[94:97], v[142:145], v[182:185], v[94:97]
	v_mfma_f32_16x16x32_bf16 v[82:85], v[134:137], v[190:193], v[82:85]
	v_mfma_f32_16x16x32_bf16 v[78:81], v[142:145], v[190:193], v[78:81]
	v_mfma_f32_16x16x32_bf16 v[130:133], v[138:141], v[170:173], v[130:133]
	v_mfma_f32_16x16x32_bf16 v[126:129], v[146:149], v[170:173], v[126:129]
	v_mfma_f32_16x16x32_bf16 v[114:117], v[138:141], v[178:181], v[114:117]
	v_mfma_f32_16x16x32_bf16 v[110:113], v[146:149], v[178:181], v[110:113]
	v_mfma_f32_16x16x32_bf16 v[98:101], v[138:141], v[186:189], v[98:101]
	v_mfma_f32_16x16x32_bf16 v[94:97], v[146:149], v[186:189], v[94:97]
	v_mfma_f32_16x16x32_bf16 v[82:85], v[138:141], v[194:197], v[82:85]
	v_mfma_f32_16x16x32_bf16 v[78:81], v[146:149], v[194:197], v[78:81]
	v_mfma_f32_16x16x32_bf16 v[122:125], v[150:153], v[166:169], v[122:125]
	v_mfma_f32_16x16x32_bf16 v[118:121], v[158:161], v[166:169], v[118:121]
	v_mfma_f32_16x16x32_bf16 v[106:109], v[150:153], v[174:177], v[106:109]
	v_mfma_f32_16x16x32_bf16 v[102:105], v[158:161], v[174:177], v[102:105]
	v_mfma_f32_16x16x32_bf16 v[90:93], v[150:153], v[182:185], v[90:93]
	v_mfma_f32_16x16x32_bf16 v[86:89], v[158:161], v[182:185], v[86:89]
	v_mfma_f32_16x16x32_bf16 v[74:77], v[150:153], v[190:193], v[74:77]
	v_mfma_f32_16x16x32_bf16 v[70:73], v[158:161], v[190:193], v[70:73]
	v_mfma_f32_16x16x32_bf16 v[122:125], v[154:157], v[170:173], v[122:125]
	v_mfma_f32_16x16x32_bf16 v[118:121], v[162:165], v[170:173], v[118:121]
	v_mfma_f32_16x16x32_bf16 v[106:109], v[154:157], v[178:181], v[106:109]
	v_mfma_f32_16x16x32_bf16 v[102:105], v[162:165], v[178:181], v[102:105]
	v_mfma_f32_16x16x32_bf16 v[90:93], v[154:157], v[186:189], v[90:93]
	v_mfma_f32_16x16x32_bf16 v[86:89], v[162:165], v[186:189], v[86:89]
	v_mfma_f32_16x16x32_bf16 v[74:77], v[154:157], v[194:197], v[74:77]
	v_mfma_f32_16x16x32_bf16 v[70:73], v[162:165], v[194:197], v[70:73]
	s_barrier
	s_add_i32 s58, s46, s31
	v_lshl_add_u64 v[218:219], s[26:27], 0, v[200:201]
	s_mov_b32 m0, s58
	ds_read_b128 v[166:169], v226 offset:16384
	ds_read_b128 v[170:173], v226 offset:17408
	ds_read_b128 v[174:177], v226 offset:18432
	ds_read_b128 v[178:181], v226 offset:19456
	ds_read_b128 v[182:185], v226 offset:20480
	ds_read_b128 v[186:189], v226 offset:21504
	ds_read_b128 v[190:193], v226 offset:22528
	ds_read_b128 v[194:197], v226 offset:23552
	global_load_lds_dwordx4 v[218:219], off
	s_add_i32 m0, s58, 0x2000
	s_add_u32 s58, s26, 0x10000
	v_lshl_add_u64 v[220:221], s[26:27], 0, v[204:205]
	s_addc_u32 s59, s27, 0
	s_add_i32 s65, s47, s31
	global_load_lds_dwordx4 v[220:221], off
	v_lshl_add_u64 v[4:5], s[58:59], 0, v[200:201]
	s_mov_b32 m0, s65
	v_lshl_add_u64 v[228:229], s[28:29], 0, v[198:199]
	global_load_lds_dwordx4 v[4:5], off
	v_lshl_add_u64 v[4:5], s[58:59], 0, v[204:205]
	s_add_i32 m0, s65, 0x2000
	v_lshl_add_u64 v[230:231], s[28:29], 0, v[202:203]
	global_load_lds_dwordx4 v[4:5], off
	s_mov_b32 m0, s33
	s_nop 0
	global_load_lds_dwordx4 v[228:229], off
	s_mov_b32 m0, s34
	s_nop 0
	global_load_lds_dwordx4 v[230:231], off
	s_waitcnt vmcnt(8)
	s_waitcnt lgkmcnt(0)
	s_barrier
; #define PG8_STAGE(bufoff, gbase, voff) do { _Pragma("unroll") for (int _i = 0; _i < 2; ++_i) \
;         __builtin_amdgcn_global_load_lds((const unsigned*)((const char*)(gbase) + (voff)[_i]), (PG8_LAS unsigned*)(lds + (bufoff) + ldsw + _i * 8192), 16, 0, 0); } while (0)
; #define PG8_LDA(dst, b, h) do { _Pragma("unroll") for (int m = 0; m < 4; ++m) _Pragma("unroll") for (int k = 0; k < 2; ++k) dst[m][k] = *(const PG8_LAS bf16x8*)(lds + PG8_SA(b, h) + aoff + m * 2048 + k * 1024); } while (0)
; #define PG8_LDB(dst, b, h) do { _Pragma("unroll") for (int n = 0; n < 2; ++n) _Pragma("unroll") for (int k = 0; k < 2; ++k) dst[n][k] = *(const PG8_LAS bf16x8*)(lds + PG8_SB(b, h) + boff + n * 2048 + k * 1024); } while (0)
; #define PG8_MMA(ai, bj, At, Bt) do { __builtin_amdgcn_s_setprio(1); _Pragma("unroll") for (int m = 0; m < 4; ++m) _Pragma("unroll") for (int n = 0; n < 2; ++n) _Pragma("unroll") for (int k = 0; k < 2; ++k) \
;         acc[ai][bj][m][n] = __builtin_amdgcn_mfma_f32_16x16x32_bf16(Bt[n][k], At[m][k], acc[ai][bj][m][n], 0, 0, 0); __builtin_amdgcn_s_setprio(0); } while (0)
; #define PG8_WAIT_V(n) asm volatile("s_waitcnt vmcnt(" #n ")" ::: "memory")
; #define PG8_WAIT_L(n) asm volatile("s_waitcnt lgkmcnt(" #n ")" ::: "memory")
; #define PG8_BAR __builtin_amdgcn_s_barrier()
; #define PG8_SCHED __builtin_amdgcn_sched_barrier(0)
; template <class Epi, class Sched, bool ALIGN_EPI = false, bool SP2 = false>
; __device__ __forceinline__ void gemm_phase(PG8_LAS unsigned char* lds, const Gemm g, const Sched& S, const Epi& E) {
;     ...
;             PG8_WAIT_V(8); PG8_WAIT_L(0); PG8_BAR; PG8_MMA(1, 0, At, B0); PG8_MMA(1, 1, At, B1); PG8_BAR; PG8_SCHED;
;             PG8_LDB(B0, 1, 0); PG8_LDB(B1, 1, 1); PG8_SCHED; PG8_LDA(At, 1, 0); PG8_STAGE(PG8_SA(0, 1), a2 + hstep, voffA);
;             PG8_WAIT_V(8); PG8_WAIT_L(0); PG8_BAR; PG8_MMA(0, 0, At, B0); PG8_MMA(0, 1, At, B1); PG8_BAR; PG8_SCHED;
	s_waitcnt lgkmcnt(0)
	v_mfma_f32_16x16x32_bf16 v[66:69], v[134:137], v[166:169], v[66:69]
	v_mfma_f32_16x16x32_bf16 v[62:65], v[142:145], v[166:169], v[62:65]
	v_mfma_f32_16x16x32_bf16 v[50:53], v[134:137], v[174:177], v[50:53]
	v_mfma_f32_16x16x32_bf16 v[46:49], v[142:145], v[174:177], v[46:49]
	v_mfma_f32_16x16x32_bf16 v[34:37], v[134:137], v[182:185], v[34:37]
	v_mfma_f32_16x16x32_bf16 v[30:33], v[142:145], v[182:185], v[30:33]
	v_mfma_f32_16x16x32_bf16 v[18:21], v[134:137], v[190:193], v[18:21]
	v_mfma_f32_16x16x32_bf16 v[14:17], v[142:145], v[190:193], v[14:17]
	v_mfma_f32_16x16x32_bf16 v[66:69], v[138:141], v[170:173], v[66:69]
	v_mfma_f32_16x16x32_bf16 v[62:65], v[146:149], v[170:173], v[62:65]
	v_mfma_f32_16x16x32_bf16 v[50:53], v[138:141], v[178:181], v[50:53]
	v_mfma_f32_16x16x32_bf16 v[46:49], v[146:149], v[178:181], v[46:49]
	v_mfma_f32_16x16x32_bf16 v[34:37], v[138:141], v[186:189], v[34:37]
	v_mfma_f32_16x16x32_bf16 v[30:33], v[146:149], v[186:189], v[30:33]
	v_mfma_f32_16x16x32_bf16 v[18:21], v[138:141], v[194:197], v[18:21]
	v_mfma_f32_16x16x32_bf16 v[14:17], v[146:149], v[194:197], v[14:17]
	v_mfma_f32_16x16x32_bf16 v[58:61], v[150:153], v[166:169], v[58:61]
	v_mfma_f32_16x16x32_bf16 v[54:57], v[158:161], v[166:169], v[54:57]
	v_mfma_f32_16x16x32_bf16 v[42:45], v[150:153], v[174:177], v[42:45]
	v_mfma_f32_16x16x32_bf16 v[38:41], v[158:161], v[174:177], v[38:41]
	v_mfma_f32_16x16x32_bf16 v[26:29], v[150:153], v[182:185], v[26:29]
	v_mfma_f32_16x16x32_bf16 v[22:25], v[158:161], v[182:185], v[22:25]
	v_mfma_f32_16x16x32_bf16 v[10:13], v[150:153], v[190:193], v[10:13]
	v_mfma_f32_16x16x32_bf16 v[4:7], v[158:161], v[190:193], v[6:9]
	v_mfma_f32_16x16x32_bf16 v[58:61], v[154:157], v[170:173], v[58:61]
	v_mfma_f32_16x16x32_bf16 v[54:57], v[162:165], v[170:173], v[54:57]
	v_mfma_f32_16x16x32_bf16 v[42:45], v[154:157], v[178:181], v[42:45]
	v_mfma_f32_16x16x32_bf16 v[38:41], v[162:165], v[178:181], v[38:41]
	v_mfma_f32_16x16x32_bf16 v[26:29], v[154:157], v[186:189], v[26:29]
	v_mfma_f32_16x16x32_bf16 v[22:25], v[162:165], v[186:189], v[22:25]
	v_mfma_f32_16x16x32_bf16 v[10:13], v[154:157], v[194:197], v[10:13]
	v_mfma_f32_16x16x32_bf16 v[4:7], v[162:165], v[194:197], v[4:7]
	s_barrier
	s_add_i32 s58, 0, 0x18000
	v_add_u32_e32 v3, s58, v224
	s_add_i32 s59, 0, 0x1c000
	ds_read_b128 v[134:137], v3
	ds_read_b128 v[138:141], v3 offset:1024
	ds_read_b128 v[142:145], v3 offset:2048
	ds_read_b128 v[146:149], v3 offset:3072
	v_add_u32_e32 v3, s59, v224
	ds_read_b128 v[150:153], v3
	ds_read_b128 v[154:157], v3 offset:1024
	ds_read_b128 v[158:161], v3 offset:2048
	ds_read_b128 v[162:165], v3 offset:3072
	s_add_u32 s28, s28, 0x40000
	s_addc_u32 s29, s29, 0
	s_mov_b32 m0, s35
	v_lshl_add_u64 v[8:9], s[28:29], 0, v[198:199]
	ds_read_b128 v[166:169], v226 offset:32768
	ds_read_b128 v[170:173], v226 offset:33792
	ds_read_b128 v[174:177], v226 offset:34816
	ds_read_b128 v[178:181], v226 offset:35840
	ds_read_b128 v[182:185], v226 offset:36864
	ds_read_b128 v[186:189], v226 offset:37888
	ds_read_b128 v[190:193], v226 offset:38912
	ds_read_b128 v[194:197], v226 offset:39936
	global_load_lds_dwordx4 v[8:9], off
	v_lshl_add_u64 v[8:9], s[28:29], 0, v[202:203]
	s_mov_b32 m0, s36
	s_nop 0
	global_load_lds_dwordx4 v[8:9], off
	s_waitcnt vmcnt(8)
	s_waitcnt lgkmcnt(0)
	s_barrier
	s_waitcnt lgkmcnt(0)
	v_mfma_f32_16x16x32_bf16 v[130:133], v[134:137], v[166:169], v[130:133]
	v_mfma_f32_16x16x32_bf16 v[126:129], v[142:145], v[166:169], v[126:129]
	v_mfma_f32_16x16x32_bf16 v[114:117], v[134:137], v[174:177], v[114:117]
	v_mfma_f32_16x16x32_bf16 v[110:113], v[142:145], v[174:177], v[110:113]
	v_mfma_f32_16x16x32_bf16 v[98:101], v[134:137], v[182:185], v[98:101]
	v_mfma_f32_16x16x32_bf16 v[94:97], v[142:145], v[182:185], v[94:97]
	v_mfma_f32_16x16x32_bf16 v[82:85], v[134:137], v[190:193], v[82:85]
	v_mfma_f32_16x16x32_bf16 v[78:81], v[142:145], v[190:193], v[78:81]
	v_mfma_f32_16x16x32_bf16 v[130:133], v[138:141], v[170:173], v[130:133]
	v_mfma_f32_16x16x32_bf16 v[126:129], v[146:149], v[170:173], v[126:129]
	v_mfma_f32_16x16x32_bf16 v[114:117], v[138:141], v[178:181], v[114:117]
	v_mfma_f32_16x16x32_bf16 v[110:113], v[146:149], v[178:181], v[110:113]
	v_mfma_f32_16x16x32_bf16 v[98:101], v[138:141], v[186:189], v[98:101]
	v_mfma_f32_16x16x32_bf16 v[94:97], v[146:149], v[186:189], v[94:97]
	v_mfma_f32_16x16x32_bf16 v[82:85], v[138:141], v[194:197], v[82:85]
	v_mfma_f32_16x16x32_bf16 v[78:81], v[146:149], v[194:197], v[78:81]
	v_mfma_f32_16x16x32_bf16 v[122:125], v[150:153], v[166:169], v[122:125]
	v_mfma_f32_16x16x32_bf16 v[118:121], v[158:161], v[166:169], v[118:121]
	v_mfma_f32_16x16x32_bf16 v[106:109], v[150:153], v[174:177], v[106:109]
	v_mfma_f32_16x16x32_bf16 v[102:105], v[158:161], v[174:177], v[102:105]
	v_mfma_f32_16x16x32_bf16 v[90:93], v[150:153], v[182:185], v[90:93]
	v_mfma_f32_16x16x32_bf16 v[86:89], v[158:161], v[182:185], v[86:89]
	v_mfma_f32_16x16x32_bf16 v[74:77], v[150:153], v[190:193], v[74:77]
	v_mfma_f32_16x16x32_bf16 v[70:73], v[158:161], v[190:193], v[70:73]
	v_mfma_f32_16x16x32_bf16 v[122:125], v[154:157], v[170:173], v[122:125]
	v_mfma_f32_16x16x32_bf16 v[118:121], v[162:165], v[170:173], v[118:121]
	v_mfma_f32_16x16x32_bf16 v[106:109], v[154:157], v[178:181], v[106:109]
	v_mfma_f32_16x16x32_bf16 v[102:105], v[162:165], v[178:181], v[102:105]
	v_mfma_f32_16x16x32_bf16 v[90:93], v[154:157], v[186:189], v[90:93]
	v_mfma_f32_16x16x32_bf16 v[86:89], v[162:165], v[186:189], v[86:89]
	v_mfma_f32_16x16x32_bf16 v[74:77], v[154:157], v[194:197], v[74:77]
	v_mfma_f32_16x16x32_bf16 v[70:73], v[162:165], v[194:197], v[70:73]
	s_barrier
; #define PG8_STAGE(bufoff, gbase, voff) do { _Pragma("unroll") for (int _i = 0; _i < 2; ++_i) \
;         __builtin_amdgcn_global_load_lds((const unsigned*)((const char*)(gbase) + (voff)[_i]), (PG8_LAS unsigned*)(lds + (bufoff) + ldsw + _i * 8192), 16, 0, 0); } while (0)
; #define PG8_LDA(dst, b, h) do { _Pragma("unroll") for (int m = 0; m < 4; ++m) _Pragma("unroll") for (int k = 0; k < 2; ++k) dst[m][k] = *(const PG8_LAS bf16x8*)(lds + PG8_SA(b, h) + aoff + m * 2048 + k * 1024); } while (0)
; #define PG8_MMA(ai, bj, At, Bt) do { __builtin_amdgcn_s_setprio(1); _Pragma("unroll") for (int m = 0; m < 4; ++m) _Pragma("unroll") for (int n = 0; n < 2; ++n) _Pragma("unroll") for (int k = 0; k < 2; ++k) \
;         acc[ai][bj][m][n] = __builtin_amdgcn_mfma_f32_16x16x32_bf16(Bt[n][k], At[m][k], acc[ai][bj][m][n], 0, 0, 0); __builtin_amdgcn_s_setprio(0); } while (0)
; #define PG8_WAIT_V(n) asm volatile("s_waitcnt vmcnt(" #n ")" ::: "memory")
; #define PG8_WAIT_L(n) asm volatile("s_waitcnt lgkmcnt(" #n ")" ::: "memory")
; #define PG8_BAR __builtin_amdgcn_s_barrier()
; #define PG8_SCHED __builtin_amdgcn_sched_barrier(0)
; template <class Epi, class Sched, bool ALIGN_EPI = false, bool SP2 = false>
; __device__ __forceinline__ void gemm_phase(PG8_LAS unsigned char* lds, const Gemm g, const Sched& S, const Epi& E) {
;     ...
;             PG8_LDA(At, 1, 1); PG8_STAGE(PG8_SB(1, 0), b3, voffB); PG8_STAGE(PG8_SB(1, 1), b3 + hstepB, voffB); PG8_STAGE(PG8_SA(1, 0), a3, voffA);
;             PG8_WAIT_V(8); PG8_WAIT_L(0); PG8_BAR; PG8_MMA(1, 0, At, B0); PG8_MMA(1, 1, At, B1); PG8_BAR; PG8_SCHED;
	s_add_i32 s28, s58, s31
	v_lshl_add_u64 v[8:9], v[218:219], 0, s[10:11]
	s_mov_b32 m0, s28
	ds_read_b128 v[166:169], v226 offset:49152
	ds_read_b128 v[170:173], v226 offset:50176
	ds_read_b128 v[174:177], v226 offset:51200
	ds_read_b128 v[178:181], v226 offset:52224
	ds_read_b128 v[182:185], v226 offset:53248
	ds_read_b128 v[186:189], v226 offset:54272
	ds_read_b128 v[190:193], v226 offset:55296
	ds_read_b128 v[194:197], v226 offset:56320
	global_load_lds_dwordx4 v[8:9], off
	s_add_i32 m0, s28, 0x2000
	s_add_u32 s26, s26, 0x10080
	v_lshl_add_u64 v[8:9], v[220:221], 0, s[10:11]
	s_addc_u32 s27, s27, 0
	s_add_i32 s28, s59, s31
	global_load_lds_dwordx4 v[8:9], off
	v_lshl_add_u64 v[8:9], s[26:27], 0, v[200:201]
	s_mov_b32 m0, s28
	s_nop 0
	global_load_lds_dwordx4 v[8:9], off
	v_lshl_add_u64 v[8:9], s[26:27], 0, v[204:205]
	s_add_i32 m0, s28, 0x2000
	s_nop 0
	global_load_lds_dwordx4 v[8:9], off
	v_lshl_add_u64 v[8:9], v[228:229], 0, s[10:11]
	s_mov_b32 m0, s39
	s_nop 0
	global_load_lds_dwordx4 v[8:9], off
	v_lshl_add_u64 v[8:9], v[230:231], 0, s[10:11]
	s_mov_b32 m0, s42
	s_nop 0
	global_load_lds_dwordx4 v[8:9], off
	s_waitcnt vmcnt(8)
	s_waitcnt lgkmcnt(0)
	s_barrier
	s_waitcnt lgkmcnt(0)
	v_mfma_f32_16x16x32_bf16 v[66:69], v[134:137], v[166:169], v[66:69]
	v_mfma_f32_16x16x32_bf16 v[62:65], v[142:145], v[166:169], v[62:65]
	v_mfma_f32_16x16x32_bf16 v[50:53], v[134:137], v[174:177], v[50:53]
	v_mfma_f32_16x16x32_bf16 v[46:49], v[142:145], v[174:177], v[46:49]
	v_mfma_f32_16x16x32_bf16 v[34:37], v[134:137], v[182:185], v[34:37]
	v_mfma_f32_16x16x32_bf16 v[30:33], v[142:145], v[182:185], v[30:33]
	v_mfma_f32_16x16x32_bf16 v[18:21], v[134:137], v[190:193], v[18:21]
	v_mfma_f32_16x16x32_bf16 v[14:17], v[142:145], v[190:193], v[14:17]
	v_mfma_f32_16x16x32_bf16 v[66:69], v[138:141], v[170:173], v[66:69]
	v_mfma_f32_16x16x32_bf16 v[62:65], v[146:149], v[170:173], v[62:65]
	v_mfma_f32_16x16x32_bf16 v[50:53], v[138:141], v[178:181], v[50:53]
	v_mfma_f32_16x16x32_bf16 v[46:49], v[146:149], v[178:181], v[46:49]
	v_mfma_f32_16x16x32_bf16 v[34:37], v[138:141], v[186:189], v[34:37]
	v_mfma_f32_16x16x32_bf16 v[30:33], v[146:149], v[186:189], v[30:33]
	v_mfma_f32_16x16x32_bf16 v[18:21], v[138:141], v[194:197], v[18:21]
	v_mfma_f32_16x16x32_bf16 v[14:17], v[146:149], v[194:197], v[14:17]
	v_mfma_f32_16x16x32_bf16 v[58:61], v[150:153], v[166:169], v[58:61]
	v_mfma_f32_16x16x32_bf16 v[54:57], v[158:161], v[166:169], v[54:57]
	v_mfma_f32_16x16x32_bf16 v[42:45], v[150:153], v[174:177], v[42:45]
	v_mfma_f32_16x16x32_bf16 v[38:41], v[158:161], v[174:177], v[38:41]
	v_mfma_f32_16x16x32_bf16 v[26:29], v[150:153], v[182:185], v[26:29]
	v_mfma_f32_16x16x32_bf16 v[22:25], v[158:161], v[182:185], v[22:25]
	v_mfma_f32_16x16x32_bf16 v[8:11], v[150:153], v[190:193], v[10:13]
	v_mfma_f32_16x16x32_bf16 v[4:7], v[158:161], v[190:193], v[4:7]
	v_mfma_f32_16x16x32_bf16 v[58:61], v[154:157], v[170:173], v[58:61]
	v_mfma_f32_16x16x32_bf16 v[54:57], v[162:165], v[170:173], v[54:57]
	v_mfma_f32_16x16x32_bf16 v[42:45], v[154:157], v[178:181], v[42:45]
	v_mfma_f32_16x16x32_bf16 v[38:41], v[162:165], v[178:181], v[38:41]
	v_mfma_f32_16x16x32_bf16 v[26:29], v[154:157], v[186:189], v[26:29]
	v_mfma_f32_16x16x32_bf16 v[22:25], v[162:165], v[186:189], v[22:25]
	v_mfma_f32_16x16x32_bf16 v[10:13], v[154:157], v[194:197], v[8:11]
	v_mfma_f32_16x16x32_bf16 v[6:9], v[162:165], v[194:197], v[4:7]
	s_barrier
	s_add_i32 s64, s64, 2
	s_add_u32 s24, s24, 0x100
	s_addc_u32 s25, s25, 0
	s_cmp_gt_u32 s64, 13
	s_cbranch_scc1 .LBB0_1097

; #define PG8_STAGE(bufoff, gbase, voff) do { _Pragma("unroll") for (int _i = 0; _i < 2; ++_i) \
;         __builtin_amdgcn_global_load_lds((const unsigned*)((const char*)(gbase) + (voff)[_i]), (PG8_LAS unsigned*)(lds + (bufoff) + ldsw + _i * 8192), 16, 0, 0); } while (0)
; #define PG8_LDA(dst, b, h) do { _Pragma("unroll") for (int m = 0; m < 4; ++m) _Pragma("unroll") for (int k = 0; k < 2; ++k) dst[m][k] = *(const PG8_LAS bf16x8*)(lds + PG8_SA(b, h) + aoff + m * 2048 + k * 1024); } while (0)
; #define PG8_LDB(dst, b, h) do { _Pragma("unroll") for (int n = 0; n < 2; ++n) _Pragma("unroll") for (int k = 0; k < 2; ++k) dst[n][k] = *(const PG8_LAS bf16x8*)(lds + PG8_SB(b, h) + boff + n * 2048 + k * 1024); } while (0)
; #define PG8_MMA(ai, bj, At, Bt) do { __builtin_amdgcn_s_setprio(1); _Pragma("unroll") for (int m = 0; m < 4; ++m) _Pragma("unroll") for (int n = 0; n < 2; ++n) _Pragma("unroll") for (int k = 0; k < 2; ++k) \
;         acc[ai][bj][m][n] = __builtin_amdgcn_mfma_f32_16x16x32_bf16(Bt[n][k], At[m][k], acc[ai][bj][m][n], 0, 0, 0); __builtin_amdgcn_s_setprio(0); } while (0)
; #define PG8_WAIT_V(n) asm volatile("s_waitcnt vmcnt(" #n ")" ::: "memory")
; #define PG8_WAIT_L(n) asm volatile("s_waitcnt lgkmcnt(" #n ")" ::: "memory")
; #define PG8_BAR __builtin_amdgcn_s_barrier()
; #define PG8_SCHED __builtin_amdgcn_sched_barrier(0)
; template <class Epi, class Sched, bool ALIGN_EPI = false, bool SP2 = false>
; __device__ __forceinline__ void gemm_phase(PG8_LAS unsigned char* lds, const Gemm g, const Sched& S, const Epi& E) {
;     ...
;             PG8_LDB(B0, 0, 0); PG8_LDB(B1, 0, 1); PG8_SCHED; PG8_LDA(At, 0, 0); PG8_STAGE(PG8_SA(1, 1), a1 + hstep, voffA);
;             PG8_WAIT_V(8); PG8_WAIT_L(0); PG8_BAR; PG8_MMA(0, 0, At, B0); PG8_MMA(0, 1, At, B1); PG8_BAR; PG8_SCHED;
;             PG8_LDA(At, 0, 1); PG8_STAGE(PG8_SB(0, 0), b2, voffB); PG8_STAGE(PG8_SB(0, 1), b2 + hstepB, voffB); PG8_STAGE(PG8_SA(0, 0), a2, voffA);
.LBB0_1180:
	v_add_u32_e32 v144, s55, v142
	ds_read_b128 v[154:157], v144
	ds_read_b128 v[158:161], v144 offset:1024
	ds_read_b128 v[162:165], v144 offset:2048
	ds_read_b128 v[166:169], v144 offset:3072
	v_add_u32_e32 v144, s56, v142
	s_add_u32 s34, s10, s28
	ds_read_b128 v[170:173], v144
	ds_read_b128 v[174:177], v144 offset:1024
	ds_read_b128 v[178:181], v144 offset:2048
	ds_read_b128 v[182:185], v144 offset:3072
	s_addc_u32 s35, s11, s29
	s_add_u32 s34, s34, 0x100
	s_addc_u32 s35, s35, 0
	s_add_u32 s61, s25, s28
	s_addc_u32 s62, s57, s29
	s_cmpk_eq_i32 s28, 0x700
	s_cselect_b32 s37, s21, s35
	s_cselect_b32 s36, s58, s34
	s_cselect_b32 s35, s19, s62
	s_cselect_b32 s34, s59, s61
	v_lshl_add_u64 v[144:145], v[138:139], 0, s[28:29]
	s_add_i32 m0, s39, 0xc000
	ds_read_b128 v[186:189], v143
	ds_read_b128 v[190:193], v143 offset:1024
	ds_read_b128 v[194:197], v143 offset:2048
	ds_read_b128 v[198:201], v143 offset:3072
	ds_read_b128 v[202:205], v143 offset:4096
	ds_read_b128 v[206:209], v143 offset:5120
	ds_read_b128 v[216:219], v143 offset:6144
	ds_read_b128 v[224:227], v143 offset:7168
	global_load_lds_dwordx4 v[144:145], off
	v_lshl_add_u64 v[144:145], v[140:141], 0, s[28:29]
	s_add_i32 m0, s39, 0xe000
	s_nop 0
	global_load_lds_dwordx4 v[144:145], off
	s_waitcnt vmcnt(8)
	s_waitcnt lgkmcnt(0)
	s_barrier
	s_waitcnt lgkmcnt(0)
	v_mfma_f32_16x16x32_bf16 v[150:153], v[154:157], v[186:189], v[150:153]
	v_mfma_f32_16x16x32_bf16 v[144:147], v[162:165], v[186:189], v[146:149]
	v_mfma_f32_16x16x32_bf16 v[110:113], v[154:157], v[194:197], v[110:113]
	v_mfma_f32_16x16x32_bf16 v[106:109], v[162:165], v[194:197], v[106:109]
	v_mfma_f32_16x16x32_bf16 v[94:97], v[154:157], v[202:205], v[94:97]
	v_mfma_f32_16x16x32_bf16 v[90:93], v[162:165], v[202:205], v[90:93]
	v_mfma_f32_16x16x32_bf16 v[78:81], v[154:157], v[216:219], v[78:81]
	v_mfma_f32_16x16x32_bf16 v[74:77], v[162:165], v[216:219], v[74:77]
	v_mfma_f32_16x16x32_bf16 v[150:153], v[158:161], v[190:193], v[150:153]
	v_mfma_f32_16x16x32_bf16 v[144:147], v[166:169], v[190:193], v[144:147]
	v_mfma_f32_16x16x32_bf16 v[110:113], v[158:161], v[198:201], v[110:113]
	v_mfma_f32_16x16x32_bf16 v[106:109], v[166:169], v[198:201], v[106:109]
	v_mfma_f32_16x16x32_bf16 v[94:97], v[158:161], v[206:209], v[94:97]
	v_mfma_f32_16x16x32_bf16 v[90:93], v[166:169], v[206:209], v[90:93]
	v_mfma_f32_16x16x32_bf16 v[78:81], v[158:161], v[224:227], v[78:81]
	v_mfma_f32_16x16x32_bf16 v[74:77], v[166:169], v[224:227], v[74:77]
	v_mfma_f32_16x16x32_bf16 v[118:121], v[170:173], v[186:189], v[118:121]
	v_mfma_f32_16x16x32_bf16 v[114:117], v[178:181], v[186:189], v[114:117]
	v_mfma_f32_16x16x32_bf16 v[102:105], v[170:173], v[194:197], v[102:105]
	v_mfma_f32_16x16x32_bf16 v[98:101], v[178:181], v[194:197], v[98:101]
	v_mfma_f32_16x16x32_bf16 v[86:89], v[170:173], v[202:205], v[86:89]
	v_mfma_f32_16x16x32_bf16 v[82:85], v[178:181], v[202:205], v[82:85]
	v_mfma_f32_16x16x32_bf16 v[70:73], v[170:173], v[216:219], v[70:73]
	v_mfma_f32_16x16x32_bf16 v[66:69], v[178:181], v[216:219], v[66:69]
	v_mfma_f32_16x16x32_bf16 v[118:121], v[174:177], v[190:193], v[118:121]
	v_mfma_f32_16x16x32_bf16 v[114:117], v[182:185], v[190:193], v[114:117]
	v_mfma_f32_16x16x32_bf16 v[102:105], v[174:177], v[198:201], v[102:105]
	v_mfma_f32_16x16x32_bf16 v[98:101], v[182:185], v[198:201], v[98:101]
	v_mfma_f32_16x16x32_bf16 v[86:89], v[174:177], v[206:209], v[86:89]
	v_mfma_f32_16x16x32_bf16 v[82:85], v[182:185], v[206:209], v[82:85]
	v_mfma_f32_16x16x32_bf16 v[70:73], v[174:177], v[224:227], v[70:73]
	v_mfma_f32_16x16x32_bf16 v[66:69], v[182:185], v[224:227], v[66:69]
	s_barrier
	s_add_i32 s61, s55, s38
	v_lshl_add_u64 v[210:211], s[34:35], 0, v[124:125]
	s_mov_b32 m0, s61
	ds_read_b128 v[186:189], v143 offset:16384
	ds_read_b128 v[190:193], v143 offset:17408
	ds_read_b128 v[194:197], v143 offset:18432
	ds_read_b128 v[198:201], v143 offset:19456
	ds_read_b128 v[202:205], v143 offset:20480
	ds_read_b128 v[206:209], v143 offset:21504
	ds_read_b128 v[216:219], v143 offset:22528
	ds_read_b128 v[224:227], v143 offset:23552
	global_load_lds_dwordx4 v[210:211], off
	s_add_i32 m0, s61, 0x2000
	s_add_u32 s62, s34, 0x10000
	v_lshl_add_u64 v[220:221], s[34:35], 0, v[128:129]
	s_addc_u32 s63, s35, 0
	s_add_i32 s61, s56, s38
	global_load_lds_dwordx4 v[220:221], off
	v_lshl_add_u64 v[148:149], s[62:63], 0, v[124:125]
	s_mov_b32 m0, s61
	v_lshl_add_u64 v[228:229], s[36:37], 0, v[122:123]
	global_load_lds_dwordx4 v[148:149], off
	v_lshl_add_u64 v[148:149], s[62:63], 0, v[128:129]
	s_add_i32 m0, s61, 0x2000
	v_lshl_add_u64 v[230:231], s[36:37], 0, v[126:127]
	global_load_lds_dwordx4 v[148:149], off
	s_mov_b32 m0, s39
	s_nop 0
	global_load_lds_dwordx4 v[228:229], off
	s_mov_b32 m0, s42
	s_nop 0
	global_load_lds_dwordx4 v[230:231], off
	s_waitcnt vmcnt(8)
	s_waitcnt lgkmcnt(0)
	s_barrier
; #define PG8_STAGE(bufoff, gbase, voff) do { _Pragma("unroll") for (int _i = 0; _i < 2; ++_i) \
;         __builtin_amdgcn_global_load_lds((const unsigned*)((const char*)(gbase) + (voff)[_i]), (PG8_LAS unsigned*)(lds + (bufoff) + ldsw + _i * 8192), 16, 0, 0); } while (0)
; #define PG8_LDA(dst, b, h) do { _Pragma("unroll") for (int m = 0; m < 4; ++m) _Pragma("unroll") for (int k = 0; k < 2; ++k) dst[m][k] = *(const PG8_LAS bf16x8*)(lds + PG8_SA(b, h) + aoff + m * 2048 + k * 1024); } while (0)
; #define PG8_LDB(dst, b, h) do { _Pragma("unroll") for (int n = 0; n < 2; ++n) _Pragma("unroll") for (int k = 0; k < 2; ++k) dst[n][k] = *(const PG8_LAS bf16x8*)(lds + PG8_SB(b, h) + boff + n * 2048 + k * 1024); } while (0)
; #define PG8_MMA(ai, bj, At, Bt) do { __builtin_amdgcn_s_setprio(1); _Pragma("unroll") for (int m = 0; m < 4; ++m) _Pragma("unroll") for (int n = 0; n < 2; ++n) _Pragma("unroll") for (int k = 0; k < 2; ++k) \
;         acc[ai][bj][m][n] = __builtin_amdgcn_mfma_f32_16x16x32_bf16(Bt[n][k], At[m][k], acc[ai][bj][m][n], 0, 0, 0); __builtin_amdgcn_s_setprio(0); } while (0)
; #define PG8_WAIT_V(n) asm volatile("s_waitcnt vmcnt(" #n ")" ::: "memory")
; #define PG8_WAIT_L(n) asm volatile("s_waitcnt lgkmcnt(" #n ")" ::: "memory")
; #define PG8_BAR __builtin_amdgcn_s_barrier()
; #define PG8_SCHED __builtin_amdgcn_sched_barrier(0)
; template <class Epi, class Sched, bool ALIGN_EPI = false, bool SP2 = false>
; __device__ __forceinline__ void gemm_phase(PG8_LAS unsigned char* lds, const Gemm g, const Sched& S, const Epi& E) {
;     ...
;             PG8_WAIT_V(8); PG8_WAIT_L(0); PG8_BAR; PG8_MMA(1, 0, At, B0); PG8_MMA(1, 1, At, B1); PG8_BAR; PG8_SCHED;
;             PG8_LDB(B0, 1, 0); PG8_LDB(B1, 1, 1); PG8_SCHED; PG8_LDA(At, 1, 0); PG8_STAGE(PG8_SA(0, 1), a2 + hstep, voffA);
;             PG8_WAIT_V(8); PG8_WAIT_L(0); PG8_BAR; PG8_MMA(0, 0, At, B0); PG8_MMA(0, 1, At, B1); PG8_BAR; PG8_SCHED;
	s_waitcnt lgkmcnt(0)
	v_mfma_f32_16x16x32_bf16 v[62:65], v[154:157], v[186:189], v[62:65]
	v_mfma_f32_16x16x32_bf16 v[58:61], v[162:165], v[186:189], v[58:61]
	v_mfma_f32_16x16x32_bf16 v[46:49], v[154:157], v[194:197], v[46:49]
	v_mfma_f32_16x16x32_bf16 v[42:45], v[162:165], v[194:197], v[42:45]
	v_mfma_f32_16x16x32_bf16 v[30:33], v[154:157], v[202:205], v[30:33]
	v_mfma_f32_16x16x32_bf16 v[26:29], v[162:165], v[202:205], v[26:29]
	v_mfma_f32_16x16x32_bf16 v[14:17], v[154:157], v[216:219], v[14:17]
	v_mfma_f32_16x16x32_bf16 v[10:13], v[162:165], v[216:219], v[10:13]
	v_mfma_f32_16x16x32_bf16 v[62:65], v[158:161], v[190:193], v[62:65]
	v_mfma_f32_16x16x32_bf16 v[58:61], v[166:169], v[190:193], v[58:61]
	v_mfma_f32_16x16x32_bf16 v[46:49], v[158:161], v[198:201], v[46:49]
	v_mfma_f32_16x16x32_bf16 v[42:45], v[166:169], v[198:201], v[42:45]
	v_mfma_f32_16x16x32_bf16 v[30:33], v[158:161], v[206:209], v[30:33]
	v_mfma_f32_16x16x32_bf16 v[26:29], v[166:169], v[206:209], v[26:29]
	v_mfma_f32_16x16x32_bf16 v[14:17], v[158:161], v[224:227], v[14:17]
	v_mfma_f32_16x16x32_bf16 v[10:13], v[166:169], v[224:227], v[10:13]
	v_mfma_f32_16x16x32_bf16 v[54:57], v[170:173], v[186:189], v[54:57]
	v_mfma_f32_16x16x32_bf16 v[50:53], v[178:181], v[186:189], v[50:53]
	v_mfma_f32_16x16x32_bf16 v[38:41], v[170:173], v[194:197], v[38:41]
	v_mfma_f32_16x16x32_bf16 v[34:37], v[178:181], v[194:197], v[34:37]
	v_mfma_f32_16x16x32_bf16 v[22:25], v[170:173], v[202:205], v[22:25]
	v_mfma_f32_16x16x32_bf16 v[18:21], v[178:181], v[202:205], v[18:21]
	v_mfma_f32_16x16x32_bf16 v[6:9], v[170:173], v[216:219], v[6:9]
	v_mfma_f32_16x16x32_bf16 v[2:5], v[178:181], v[216:219], v[2:5]
	v_mfma_f32_16x16x32_bf16 v[54:57], v[174:177], v[190:193], v[54:57]
	v_mfma_f32_16x16x32_bf16 v[50:53], v[182:185], v[190:193], v[50:53]
	v_mfma_f32_16x16x32_bf16 v[38:41], v[174:177], v[198:201], v[38:41]
	v_mfma_f32_16x16x32_bf16 v[34:37], v[182:185], v[198:201], v[34:37]
	v_mfma_f32_16x16x32_bf16 v[22:25], v[174:177], v[206:209], v[22:25]
	v_mfma_f32_16x16x32_bf16 v[18:21], v[182:185], v[206:209], v[18:21]
	v_mfma_f32_16x16x32_bf16 v[6:9], v[174:177], v[224:227], v[6:9]
	v_mfma_f32_16x16x32_bf16 v[2:5], v[182:185], v[224:227], v[2:5]
	s_barrier
	s_add_i32 s61, 0, 0x18000
	v_add_u32_e32 v148, s61, v142
	s_add_i32 s62, 0, 0x1c000
	ds_read_b128 v[154:157], v148
	ds_read_b128 v[158:161], v148 offset:1024
	ds_read_b128 v[162:165], v148 offset:2048
	ds_read_b128 v[166:169], v148 offset:3072
	v_add_u32_e32 v148, s62, v142
	ds_read_b128 v[170:173], v148
	ds_read_b128 v[174:177], v148 offset:1024
	ds_read_b128 v[178:181], v148 offset:2048
	ds_read_b128 v[182:185], v148 offset:3072
	s_add_u32 s36, s36, 0x40000
	s_addc_u32 s37, s37, 0
	s_mov_b32 m0, s44
	v_lshl_add_u64 v[148:149], s[36:37], 0, v[122:123]
	ds_read_b128 v[186:189], v143 offset:32768
	ds_read_b128 v[190:193], v143 offset:33792
	ds_read_b128 v[194:197], v143 offset:34816
	ds_read_b128 v[198:201], v143 offset:35840
	ds_read_b128 v[202:205], v143 offset:36864
	ds_read_b128 v[206:209], v143 offset:37888
	ds_read_b128 v[216:219], v143 offset:38912
	ds_read_b128 v[224:227], v143 offset:39936
	global_load_lds_dwordx4 v[148:149], off
	v_lshl_add_u64 v[148:149], s[36:37], 0, v[126:127]
	s_mov_b32 m0, s45
	s_nop 0
	global_load_lds_dwordx4 v[148:149], off
	s_waitcnt vmcnt(8)
	s_waitcnt lgkmcnt(0)
	s_barrier
	s_waitcnt lgkmcnt(0)
	v_mfma_f32_16x16x32_bf16 v[148:151], v[154:157], v[186:189], v[150:153]
	v_mfma_f32_16x16x32_bf16 v[144:147], v[162:165], v[186:189], v[144:147]
	v_mfma_f32_16x16x32_bf16 v[110:113], v[154:157], v[194:197], v[110:113]
	v_mfma_f32_16x16x32_bf16 v[106:109], v[162:165], v[194:197], v[106:109]
	v_mfma_f32_16x16x32_bf16 v[94:97], v[154:157], v[202:205], v[94:97]
	v_mfma_f32_16x16x32_bf16 v[90:93], v[162:165], v[202:205], v[90:93]
	v_mfma_f32_16x16x32_bf16 v[78:81], v[154:157], v[216:219], v[78:81]
	v_mfma_f32_16x16x32_bf16 v[74:77], v[162:165], v[216:219], v[74:77]
	v_mfma_f32_16x16x32_bf16 v[150:153], v[158:161], v[190:193], v[148:151]
	v_mfma_f32_16x16x32_bf16 v[146:149], v[166:169], v[190:193], v[144:147]
	v_mfma_f32_16x16x32_bf16 v[110:113], v[158:161], v[198:201], v[110:113]
	v_mfma_f32_16x16x32_bf16 v[106:109], v[166:169], v[198:201], v[106:109]
	v_mfma_f32_16x16x32_bf16 v[94:97], v[158:161], v[206:209], v[94:97]
	v_mfma_f32_16x16x32_bf16 v[90:93], v[166:169], v[206:209], v[90:93]
	v_mfma_f32_16x16x32_bf16 v[78:81], v[158:161], v[224:227], v[78:81]
	v_mfma_f32_16x16x32_bf16 v[74:77], v[166:169], v[224:227], v[74:77]
	v_mfma_f32_16x16x32_bf16 v[118:121], v[170:173], v[186:189], v[118:121]
	v_mfma_f32_16x16x32_bf16 v[114:117], v[178:181], v[186:189], v[114:117]
	v_mfma_f32_16x16x32_bf16 v[102:105], v[170:173], v[194:197], v[102:105]
	v_mfma_f32_16x16x32_bf16 v[98:101], v[178:181], v[194:197], v[98:101]
	v_mfma_f32_16x16x32_bf16 v[86:89], v[170:173], v[202:205], v[86:89]
	v_mfma_f32_16x16x32_bf16 v[82:85], v[178:181], v[202:205], v[82:85]
	v_mfma_f32_16x16x32_bf16 v[70:73], v[170:173], v[216:219], v[70:73]
	v_mfma_f32_16x16x32_bf16 v[66:69], v[178:181], v[216:219], v[66:69]
	v_mfma_f32_16x16x32_bf16 v[118:121], v[174:177], v[190:193], v[118:121]
	v_mfma_f32_16x16x32_bf16 v[114:117], v[182:185], v[190:193], v[114:117]
	v_mfma_f32_16x16x32_bf16 v[102:105], v[174:177], v[198:201], v[102:105]
	v_mfma_f32_16x16x32_bf16 v[98:101], v[182:185], v[198:201], v[98:101]
	v_mfma_f32_16x16x32_bf16 v[86:89], v[174:177], v[206:209], v[86:89]
	v_mfma_f32_16x16x32_bf16 v[82:85], v[182:185], v[206:209], v[82:85]
	v_mfma_f32_16x16x32_bf16 v[70:73], v[174:177], v[224:227], v[70:73]
	v_mfma_f32_16x16x32_bf16 v[66:69], v[182:185], v[224:227], v[66:69]
	s_barrier
; #define PG8_STAGE(bufoff, gbase, voff) do { _Pragma("unroll") for (int _i = 0; _i < 2; ++_i) \
;         __builtin_amdgcn_global_load_lds((const unsigned*)((const char*)(gbase) + (voff)[_i]), (PG8_LAS unsigned*)(lds + (bufoff) + ldsw + _i * 8192), 16, 0, 0); } while (0)
; #define PG8_LDA(dst, b, h) do { _Pragma("unroll") for (int m = 0; m < 4; ++m) _Pragma("unroll") for (int k = 0; k < 2; ++k) dst[m][k] = *(const PG8_LAS bf16x8*)(lds + PG8_SA(b, h) + aoff + m * 2048 + k * 1024); } while (0)
; #define PG8_MMA(ai, bj, At, Bt) do { __builtin_amdgcn_s_setprio(1); _Pragma("unroll") for (int m = 0; m < 4; ++m) _Pragma("unroll") for (int n = 0; n < 2; ++n) _Pragma("unroll") for (int k = 0; k < 2; ++k) \
;         acc[ai][bj][m][n] = __builtin_amdgcn_mfma_f32_16x16x32_bf16(Bt[n][k], At[m][k], acc[ai][bj][m][n], 0, 0, 0); __builtin_amdgcn_s_setprio(0); } while (0)
; #define PG8_WAIT_V(n) asm volatile("s_waitcnt vmcnt(" #n ")" ::: "memory")
; #define PG8_WAIT_L(n) asm volatile("s_waitcnt lgkmcnt(" #n ")" ::: "memory")
; #define PG8_BAR __builtin_amdgcn_s_barrier()
; #define PG8_SCHED __builtin_amdgcn_sched_barrier(0)
; template <class Epi, class Sched, bool ALIGN_EPI = false, bool SP2 = false>
; __device__ __forceinline__ void gemm_phase(PG8_LAS unsigned char* lds, const Gemm g, const Sched& S, const Epi& E) {
;     ...
;             PG8_LDA(At, 1, 1); PG8_STAGE(PG8_SB(1, 0), b3, voffB); PG8_STAGE(PG8_SB(1, 1), b3 + hstepB, voffB); PG8_STAGE(PG8_SA(1, 0), a3, voffA);
;             PG8_WAIT_V(8); PG8_WAIT_L(0); PG8_BAR; PG8_MMA(1, 0, At, B0); PG8_MMA(1, 1, At, B1); PG8_BAR; PG8_SCHED;
;     ...
; #pragma unroll
;         for (int a = 0; a < 2; ++a)
; #pragma unroll
;             for (int b = 0; b < 2; ++b)
; #pragma unroll
;                 for (int m = 0; m < 4; ++m)
; #pragma unroll
;                     for (int n = 0; n < 2; ++n) acc[a][b][m][n] = (f32x4){0.f, 0.f, 0.f, 0.f};
;         cur = nxt; cA = nA; cB = nB; ++ui;
	s_add_i32 s36, s61, s38
	v_lshl_add_u64 v[144:145], v[210:211], 0, s[16:17]
	s_mov_b32 m0, s36
	ds_read_b128 v[186:189], v143 offset:49152
	ds_read_b128 v[190:193], v143 offset:50176
	ds_read_b128 v[194:197], v143 offset:51200
	ds_read_b128 v[198:201], v143 offset:52224
	ds_read_b128 v[202:205], v143 offset:53248
	ds_read_b128 v[206:209], v143 offset:54272
	ds_read_b128 v[216:219], v143 offset:55296
	ds_read_b128 v[224:227], v143 offset:56320
	global_load_lds_dwordx4 v[144:145], off
	s_add_i32 m0, s36, 0x2000
	s_add_u32 s34, s34, 0x10080
	v_lshl_add_u64 v[144:145], v[220:221], 0, s[16:17]
	s_addc_u32 s35, s35, 0
	s_add_i32 s36, s62, s38
	global_load_lds_dwordx4 v[144:145], off
	v_lshl_add_u64 v[144:145], s[34:35], 0, v[124:125]
	s_mov_b32 m0, s36
	s_nop 0
	global_load_lds_dwordx4 v[144:145], off
	v_lshl_add_u64 v[144:145], s[34:35], 0, v[128:129]
	s_add_i32 m0, s36, 0x2000
	s_nop 0
	global_load_lds_dwordx4 v[144:145], off
	v_lshl_add_u64 v[144:145], v[228:229], 0, s[16:17]
	s_mov_b32 m0, s46
	s_nop 0
	global_load_lds_dwordx4 v[144:145], off
	v_lshl_add_u64 v[144:145], v[230:231], 0, s[16:17]
	s_mov_b32 m0, s47
	s_nop 0
	global_load_lds_dwordx4 v[144:145], off
	s_waitcnt vmcnt(8)
	s_waitcnt lgkmcnt(0)
	s_barrier
	s_waitcnt lgkmcnt(0)
	v_mfma_f32_16x16x32_bf16 v[62:65], v[154:157], v[186:189], v[62:65]
	v_mfma_f32_16x16x32_bf16 v[58:61], v[162:165], v[186:189], v[58:61]
	v_mfma_f32_16x16x32_bf16 v[46:49], v[154:157], v[194:197], v[46:49]
	v_mfma_f32_16x16x32_bf16 v[42:45], v[162:165], v[194:197], v[42:45]
	v_mfma_f32_16x16x32_bf16 v[30:33], v[154:157], v[202:205], v[30:33]
	v_mfma_f32_16x16x32_bf16 v[26:29], v[162:165], v[202:205], v[26:29]
	v_mfma_f32_16x16x32_bf16 v[14:17], v[154:157], v[216:219], v[14:17]
	v_mfma_f32_16x16x32_bf16 v[10:13], v[162:165], v[216:219], v[10:13]
	v_mfma_f32_16x16x32_bf16 v[62:65], v[158:161], v[190:193], v[62:65]
	v_mfma_f32_16x16x32_bf16 v[58:61], v[166:169], v[190:193], v[58:61]
	v_mfma_f32_16x16x32_bf16 v[46:49], v[158:161], v[198:201], v[46:49]
	v_mfma_f32_16x16x32_bf16 v[42:45], v[166:169], v[198:201], v[42:45]
	v_mfma_f32_16x16x32_bf16 v[30:33], v[158:161], v[206:209], v[30:33]
	v_mfma_f32_16x16x32_bf16 v[26:29], v[166:169], v[206:209], v[26:29]
	v_mfma_f32_16x16x32_bf16 v[14:17], v[158:161], v[224:227], v[14:17]
	v_mfma_f32_16x16x32_bf16 v[10:13], v[166:169], v[224:227], v[10:13]
	v_mfma_f32_16x16x32_bf16 v[54:57], v[170:173], v[186:189], v[54:57]
	v_mfma_f32_16x16x32_bf16 v[50:53], v[178:181], v[186:189], v[50:53]
	v_mfma_f32_16x16x32_bf16 v[38:41], v[170:173], v[194:197], v[38:41]
	v_mfma_f32_16x16x32_bf16 v[34:37], v[178:181], v[194:197], v[34:37]
	v_mfma_f32_16x16x32_bf16 v[22:25], v[170:173], v[202:205], v[22:25]
	v_mfma_f32_16x16x32_bf16 v[18:21], v[178:181], v[202:205], v[18:21]
	v_mfma_f32_16x16x32_bf16 v[6:9], v[170:173], v[216:219], v[6:9]
	v_mfma_f32_16x16x32_bf16 v[2:5], v[178:181], v[216:219], v[2:5]
	v_mfma_f32_16x16x32_bf16 v[54:57], v[174:177], v[190:193], v[54:57]
	v_mfma_f32_16x16x32_bf16 v[50:53], v[182:185], v[190:193], v[50:53]
	v_mfma_f32_16x16x32_bf16 v[38:41], v[174:177], v[198:201], v[38:41]
	v_mfma_f32_16x16x32_bf16 v[34:37], v[182:185], v[198:201], v[34:37]
	v_mfma_f32_16x16x32_bf16 v[22:25], v[174:177], v[206:209], v[22:25]
	v_mfma_f32_16x16x32_bf16 v[18:21], v[182:185], v[206:209], v[18:21]
	v_mfma_f32_16x16x32_bf16 v[6:9], v[174:177], v[224:227], v[6:9]
	v_mfma_f32_16x16x32_bf16 v[2:5], v[182:185], v[224:227], v[2:5]
	s_barrier
	s_add_i32 s60, s60, 2
	s_add_u32 s28, s28, 0x100
	s_addc_u32 s29, s29, 0
	s_cmp_gt_u32 s60, 13
	s_cbranch_scc0 .LBB0_1180
	s_add_u32 s28, s25, 0xffffff00
	s_addc_u32 s29, s57, -1
	s_andn2_b64 vcc, exec, s[8:9]
	s_cbranch_vccnz .LBB0_1171
	v_mov_b32_e32 v2, 0
	s_mov_b32 s0, s18
	s_mov_b32 s14, s20
	s_mov_b64 s[10:11], s[26:27]
	s_mov_b32 s54, s24
	v_mov_b32_e32 v3, v2
	v_mov_b32_e32 v4, v2
	v_mov_b32_e32 v5, v2
	v_mov_b32_e32 v6, v2
	v_mov_b32_e32 v7, v2
	v_mov_b32_e32 v8, v2
	v_mov_b32_e32 v9, v2
	v_mov_b32_e32 v18, v2
	v_mov_b32_e32 v19, v2
	v_mov_b32_e32 v20, v2
	v_mov_b32_e32 v21, v2
	v_mov_b32_e32 v22, v2
	v_mov_b32_e32 v23, v2
	v_mov_b32_e32 v24, v2
	v_mov_b32_e32 v25, v2
	v_mov_b32_e32 v34, v2
	v_mov_b32_e32 v35, v2
	v_mov_b32_e32 v36, v2
	v_mov_b32_e32 v37, v2
	v_mov_b32_e32 v38, v2
	v_mov_b32_e32 v39, v2
	v_mov_b32_e32 v40, v2
	v_mov_b32_e32 v41, v2
	v_mov_b32_e32 v50, v2
	v_mov_b32_e32 v51, v2
	v_mov_b32_e32 v52, v2
	v_mov_b32_e32 v53, v2
	v_mov_b32_e32 v54, v2
	v_mov_b32_e32 v55, v2
	v_mov_b32_e32 v56, v2
	v_mov_b32_e32 v57, v2
	v_mov_b32_e32 v10, v2
	v_mov_b32_e32 v11, v2
	v_mov_b32_e32 v12, v2
	v_mov_b32_e32 v13, v2
	v_mov_b32_e32 v14, v2
	v_mov_b32_e32 v15, v2
	v_mov_b32_e32 v16, v2
	v_mov_b32_e32 v17, v2
	v_mov_b32_e32 v26, v2
	v_mov_b32_e32 v27, v2
	v_mov_b32_e32 v28, v2
	v_mov_b32_e32 v29, v2
	v_mov_b32_e32 v30, v2
	v_mov_b32_e32 v31, v2
	v_mov_b32_e32 v32, v2
	v_mov_b32_e32 v33, v2
	v_mov_b32_e32 v42, v2
	v_mov_b32_e32 v43, v2
	v_mov_b32_e32 v44, v2
	v_mov_b32_e32 v45, v2
	v_mov_b32_e32 v46, v2
	v_mov_b32_e32 v47, v2
	v_mov_b32_e32 v48, v2
	v_mov_b32_e32 v49, v2
	v_mov_b32_e32 v58, v2
	v_mov_b32_e32 v59, v2
	v_mov_b32_e32 v60, v2
	v_mov_b32_e32 v61, v2
	v_mov_b32_e32 v62, v2
	v_mov_b32_e32 v63, v2
	v_mov_b32_e32 v64, v2
	v_mov_b32_e32 v65, v2
	v_mov_b32_e32 v66, v2
	v_mov_b32_e32 v67, v2
	v_mov_b32_e32 v68, v2
	v_mov_b32_e32 v69, v2
	v_mov_b32_e32 v70, v2
	v_mov_b32_e32 v71, v2
	v_mov_b32_e32 v72, v2
	v_mov_b32_e32 v73, v2
	v_mov_b32_e32 v82, v2
	v_mov_b32_e32 v83, v2
	v_mov_b32_e32 v84, v2
	v_mov_b32_e32 v85, v2
	v_mov_b32_e32 v86, v2
	v_mov_b32_e32 v87, v2
	v_mov_b32_e32 v88, v2
	v_mov_b32_e32 v89, v2
	v_mov_b32_e32 v98, v2
	v_mov_b32_e32 v99, v2
	v_mov_b32_e32 v100, v2
	v_mov_b32_e32 v101, v2
	v_mov_b32_e32 v102, v2
	v_mov_b32_e32 v103, v2
	v_mov_b32_e32 v104, v2
	v_mov_b32_e32 v105, v2
	v_mov_b32_e32 v114, v2
	v_mov_b32_e32 v115, v2
	v_mov_b32_e32 v116, v2
	v_mov_b32_e32 v117, v2
	v_mov_b32_e32 v118, v2
	v_mov_b32_e32 v119, v2
	v_mov_b32_e32 v120, v2
	v_mov_b32_e32 v121, v2
	v_mov_b32_e32 v74, v2
	v_mov_b32_e32 v75, v2
	v_mov_b32_e32 v76, v2
	v_mov_b32_e32 v77, v2
	v_mov_b32_e32 v78, v2
	v_mov_b32_e32 v79, v2
	v_mov_b32_e32 v80, v2
	v_mov_b32_e32 v81, v2
	v_mov_b32_e32 v90, v2
	v_mov_b32_e32 v91, v2
	v_mov_b32_e32 v92, v2
	v_mov_b32_e32 v93, v2
	v_mov_b32_e32 v94, v2
	v_mov_b32_e32 v95, v2
	v_mov_b32_e32 v96, v2
	v_mov_b32_e32 v97, v2
	v_mov_b32_e32 v106, v2
	v_mov_b32_e32 v107, v2
	v_mov_b32_e32 v108, v2
	v_mov_b32_e32 v109, v2
	v_mov_b32_e32 v110, v2
	v_mov_b32_e32 v111, v2
	v_mov_b32_e32 v112, v2
	v_mov_b32_e32 v113, v2
	v_mov_b32_e32 v146, v2
	v_mov_b32_e32 v147, v2
	v_mov_b32_e32 v148, v2
	v_mov_b32_e32 v149, v2
	v_mov_b32_e32 v150, v2
	v_mov_b32_e32 v151, v2
	v_mov_b32_e32 v152, v2
	v_mov_b32_e32 v153, v2
	s_andn2_b64 vcc, exec, s[6:7]
	s_cbranch_vccnz .LBB0_1172

; #define PG8_STAGE(bufoff, gbase, voff) do { _Pragma("unroll") for (int _i = 0; _i < 2; ++_i) \
;         __builtin_amdgcn_global_load_lds((const unsigned*)((const char*)(gbase) + (voff)[_i]), (PG8_LAS unsigned*)(lds + (bufoff) + ldsw + _i * 8192), 16, 0, 0); } while (0)
; #define PG8_LDA(dst, b, h) do { _Pragma("unroll") for (int m = 0; m < 4; ++m) _Pragma("unroll") for (int k = 0; k < 2; ++k) dst[m][k] = *(const PG8_LAS bf16x8*)(lds + PG8_SA(b, h) + aoff + m * 2048 + k * 1024); } while (0)
; #define PG8_LDB(dst, b, h) do { _Pragma("unroll") for (int n = 0; n < 2; ++n) _Pragma("unroll") for (int k = 0; k < 2; ++k) dst[n][k] = *(const PG8_LAS bf16x8*)(lds + PG8_SB(b, h) + boff + n * 2048 + k * 1024); } while (0)
; #define PG8_MMA(ai, bj, At, Bt) do { __builtin_amdgcn_s_setprio(1); _Pragma("unroll") for (int m = 0; m < 4; ++m) _Pragma("unroll") for (int n = 0; n < 2; ++n) _Pragma("unroll") for (int k = 0; k < 2; ++k) \
;         acc[ai][bj][m][n] = __builtin_amdgcn_mfma_f32_16x16x32_bf16(Bt[n][k], At[m][k], acc[ai][bj][m][n], 0, 0, 0); __builtin_amdgcn_s_setprio(0); } while (0)
; #define PG8_WAIT_V(n) asm volatile("s_waitcnt vmcnt(" #n ")" ::: "memory")
; #define PG8_WAIT_L(n) asm volatile("s_waitcnt lgkmcnt(" #n ")" ::: "memory")
; #define PG8_BAR __builtin_amdgcn_s_barrier()
; #define PG8_SCHED __builtin_amdgcn_sched_barrier(0)
; template <class Epi, class Sched, bool ALIGN_EPI = false, bool SP2 = false>
; __device__ __forceinline__ void gemm_phase(PG8_LAS unsigned char* lds, const Gemm g, const Sched& S, const Epi& E) {
;     ...
;             PG8_LDB(B0, 0, 0); PG8_LDB(B1, 0, 1); PG8_SCHED; PG8_LDA(At, 0, 0); PG8_STAGE(PG8_SA(1, 1), a1 + hstep, voffA);
;             PG8_WAIT_V(8); PG8_WAIT_L(0); PG8_BAR; PG8_MMA(0, 0, At, B0); PG8_MMA(0, 1, At, B1); PG8_BAR; PG8_SCHED;
;             PG8_LDA(At, 0, 1); PG8_STAGE(PG8_SB(0, 0), b2, voffB); PG8_STAGE(PG8_SB(0, 1), b2 + hstepB, voffB); PG8_STAGE(PG8_SA(0, 0), a2, voffA);
.LBB0_1313:
	ds_read_b128 v[146:149], v154
	ds_read_b128 v[158:161], v154 offset:1024
	ds_read_b128 v[162:165], v154 offset:2048
	ds_read_b128 v[166:169], v154 offset:3072
	ds_read_b128 v[170:173], v155
	ds_read_b128 v[174:177], v155 offset:1024
	ds_read_b128 v[178:181], v155 offset:2048
	ds_read_b128 v[182:185], v155 offset:3072
	s_add_u32 s40, s38, 0xfffc0080
	s_addc_u32 s41, s39, -1
	s_cmp_eq_u32 s61, 12
	s_cselect_b32 s43, s9, s41
	s_cselect_b32 s42, s27, s40
	s_cselect_b32 s41, s25, s60
	s_cselect_b32 s40, s37, s59
	v_lshl_add_u64 v[150:151], s[38:39], 0, v[138:139]
	s_add_i32 m0, s31, 0xc000
	ds_read_b128 v[186:189], v156
	ds_read_b128 v[190:193], v156 offset:1024
	ds_read_b128 v[194:197], v156 offset:2048
	ds_read_b128 v[198:201], v156 offset:3072
	ds_read_b128 v[202:205], v156 offset:4096
	ds_read_b128 v[206:209], v156 offset:5120
	ds_read_b128 v[210:213], v156 offset:6144
	ds_read_b128 v[214:217], v156 offset:7168
	global_load_lds_dwordx4 v[150:151], off
	v_lshl_add_u64 v[150:151], s[38:39], 0, v[140:141]
	s_add_i32 m0, s31, 0xe000
	s_nop 0
	global_load_lds_dwordx4 v[150:151], off
	s_waitcnt vmcnt(8)
	s_waitcnt lgkmcnt(0)
	s_barrier
	s_waitcnt lgkmcnt(0)
	v_mfma_f32_16x16x32_bf16 v[126:129], v[146:149], v[186:189], v[126:129]
	v_mfma_f32_16x16x32_bf16 v[122:125], v[162:165], v[186:189], v[122:125]
	v_mfma_f32_16x16x32_bf16 v[110:113], v[146:149], v[194:197], v[110:113]
	v_mfma_f32_16x16x32_bf16 v[106:109], v[162:165], v[194:197], v[106:109]
	v_mfma_f32_16x16x32_bf16 v[94:97], v[146:149], v[202:205], v[94:97]
	v_mfma_f32_16x16x32_bf16 v[90:93], v[162:165], v[202:205], v[90:93]
	v_mfma_f32_16x16x32_bf16 v[78:81], v[146:149], v[210:213], v[78:81]
	v_mfma_f32_16x16x32_bf16 v[74:77], v[162:165], v[210:213], v[74:77]
	v_mfma_f32_16x16x32_bf16 v[126:129], v[158:161], v[190:193], v[126:129]
	v_mfma_f32_16x16x32_bf16 v[122:125], v[166:169], v[190:193], v[122:125]
	v_mfma_f32_16x16x32_bf16 v[110:113], v[158:161], v[198:201], v[110:113]
	v_mfma_f32_16x16x32_bf16 v[106:109], v[166:169], v[198:201], v[106:109]
	v_mfma_f32_16x16x32_bf16 v[94:97], v[158:161], v[206:209], v[94:97]
	v_mfma_f32_16x16x32_bf16 v[90:93], v[166:169], v[206:209], v[90:93]
	v_mfma_f32_16x16x32_bf16 v[78:81], v[158:161], v[214:217], v[78:81]
	v_mfma_f32_16x16x32_bf16 v[74:77], v[166:169], v[214:217], v[74:77]
	v_mfma_f32_16x16x32_bf16 v[118:121], v[170:173], v[186:189], v[118:121]
	v_mfma_f32_16x16x32_bf16 v[114:117], v[178:181], v[186:189], v[114:117]
	v_mfma_f32_16x16x32_bf16 v[102:105], v[170:173], v[194:197], v[102:105]
	v_mfma_f32_16x16x32_bf16 v[98:101], v[178:181], v[194:197], v[98:101]
	v_mfma_f32_16x16x32_bf16 v[86:89], v[170:173], v[202:205], v[86:89]
	v_mfma_f32_16x16x32_bf16 v[82:85], v[178:181], v[202:205], v[82:85]
	v_mfma_f32_16x16x32_bf16 v[70:73], v[170:173], v[210:213], v[70:73]
	v_mfma_f32_16x16x32_bf16 v[66:69], v[178:181], v[210:213], v[66:69]
	v_mfma_f32_16x16x32_bf16 v[118:121], v[174:177], v[190:193], v[118:121]
	v_mfma_f32_16x16x32_bf16 v[114:117], v[182:185], v[190:193], v[114:117]
	v_mfma_f32_16x16x32_bf16 v[102:105], v[174:177], v[198:201], v[102:105]
	v_mfma_f32_16x16x32_bf16 v[98:101], v[182:185], v[198:201], v[98:101]
	v_mfma_f32_16x16x32_bf16 v[86:89], v[174:177], v[206:209], v[86:89]
	v_mfma_f32_16x16x32_bf16 v[82:85], v[182:185], v[206:209], v[82:85]
	v_mfma_f32_16x16x32_bf16 v[70:73], v[174:177], v[214:217], v[70:73]
	v_mfma_f32_16x16x32_bf16 v[66:69], v[182:185], v[214:217], v[66:69]
	s_barrier
	s_add_i32 s62, s57, s30
	v_lshl_add_u64 v[150:151], s[40:41], 0, v[132:133]
	s_mov_b32 m0, s62
	ds_read_b128 v[186:189], v156 offset:16384
	ds_read_b128 v[190:193], v156 offset:17408
	ds_read_b128 v[194:197], v156 offset:18432
	ds_read_b128 v[198:201], v156 offset:19456
	ds_read_b128 v[202:205], v156 offset:20480
	ds_read_b128 v[206:209], v156 offset:21504
	ds_read_b128 v[210:213], v156 offset:22528
	ds_read_b128 v[214:217], v156 offset:23552
	global_load_lds_dwordx4 v[150:151], off
	s_add_i32 m0, s62, 0x2000
	s_add_u32 s62, s40, 0x10000
	v_lshl_add_u64 v[218:219], s[40:41], 0, v[136:137]
	s_addc_u32 s63, s41, 0
	s_add_i32 s64, s58, s30
	global_load_lds_dwordx4 v[218:219], off
	v_lshl_add_u64 v[220:221], s[62:63], 0, v[132:133]
	s_mov_b32 m0, s64
	v_lshl_add_u64 v[222:223], s[42:43], 0, v[134:135]
	global_load_lds_dwordx4 v[220:221], off
	v_lshl_add_u64 v[220:221], s[62:63], 0, v[136:137]
	s_add_i32 m0, s64, 0x2000
	s_nop 0
	global_load_lds_dwordx4 v[220:221], off
	v_lshl_add_u64 v[220:221], s[42:43], 0, v[130:131]
	s_mov_b32 m0, s31
	s_nop 0
	global_load_lds_dwordx4 v[220:221], off
	s_mov_b32 m0, s33
	s_nop 0
	global_load_lds_dwordx4 v[222:223], off
	s_waitcnt vmcnt(8)
	s_waitcnt lgkmcnt(0)
	s_barrier
; #define PG8_STAGE(bufoff, gbase, voff) do { _Pragma("unroll") for (int _i = 0; _i < 2; ++_i) \
;         __builtin_amdgcn_global_load_lds((const unsigned*)((const char*)(gbase) + (voff)[_i]), (PG8_LAS unsigned*)(lds + (bufoff) + ldsw + _i * 8192), 16, 0, 0); } while (0)
; #define PG8_LDA(dst, b, h) do { _Pragma("unroll") for (int m = 0; m < 4; ++m) _Pragma("unroll") for (int k = 0; k < 2; ++k) dst[m][k] = *(const PG8_LAS bf16x8*)(lds + PG8_SA(b, h) + aoff + m * 2048 + k * 1024); } while (0)
; #define PG8_LDB(dst, b, h) do { _Pragma("unroll") for (int n = 0; n < 2; ++n) _Pragma("unroll") for (int k = 0; k < 2; ++k) dst[n][k] = *(const PG8_LAS bf16x8*)(lds + PG8_SB(b, h) + boff + n * 2048 + k * 1024); } while (0)
; #define PG8_MMA(ai, bj, At, Bt) do { __builtin_amdgcn_s_setprio(1); _Pragma("unroll") for (int m = 0; m < 4; ++m) _Pragma("unroll") for (int n = 0; n < 2; ++n) _Pragma("unroll") for (int k = 0; k < 2; ++k) \
;         acc[ai][bj][m][n] = __builtin_amdgcn_mfma_f32_16x16x32_bf16(Bt[n][k], At[m][k], acc[ai][bj][m][n], 0, 0, 0); __builtin_amdgcn_s_setprio(0); } while (0)
; #define PG8_WAIT_V(n) asm volatile("s_waitcnt vmcnt(" #n ")" ::: "memory")
; #define PG8_WAIT_L(n) asm volatile("s_waitcnt lgkmcnt(" #n ")" ::: "memory")
; #define PG8_BAR __builtin_amdgcn_s_barrier()
; #define PG8_SCHED __builtin_amdgcn_sched_barrier(0)
; template <class Epi, class Sched, bool ALIGN_EPI = false, bool SP2 = false>
; __device__ __forceinline__ void gemm_phase(PG8_LAS unsigned char* lds, const Gemm g, const Sched& S, const Epi& E) {
;     ...
;             PG8_WAIT_V(8); PG8_WAIT_L(0); PG8_BAR; PG8_MMA(1, 0, At, B0); PG8_MMA(1, 1, At, B1); PG8_BAR; PG8_SCHED;
;             PG8_LDB(B0, 1, 0); PG8_LDB(B1, 1, 1); PG8_SCHED; PG8_LDA(At, 1, 0); PG8_STAGE(PG8_SA(0, 1), a2 + hstep, voffA);
;             PG8_WAIT_V(8); PG8_WAIT_L(0); PG8_BAR; PG8_MMA(0, 0, At, B0); PG8_MMA(0, 1, At, B1); PG8_BAR; PG8_SCHED;
	s_waitcnt lgkmcnt(0)
	v_mfma_f32_16x16x32_bf16 v[62:65], v[146:149], v[186:189], v[62:65]
	v_mfma_f32_16x16x32_bf16 v[58:61], v[162:165], v[186:189], v[58:61]
	v_mfma_f32_16x16x32_bf16 v[46:49], v[146:149], v[194:197], v[46:49]
	v_mfma_f32_16x16x32_bf16 v[42:45], v[162:165], v[194:197], v[42:45]
	v_mfma_f32_16x16x32_bf16 v[30:33], v[146:149], v[202:205], v[30:33]
	v_mfma_f32_16x16x32_bf16 v[26:29], v[162:165], v[202:205], v[26:29]
	v_mfma_f32_16x16x32_bf16 v[14:17], v[146:149], v[210:213], v[14:17]
	v_mfma_f32_16x16x32_bf16 v[10:13], v[162:165], v[210:213], v[10:13]
	v_mfma_f32_16x16x32_bf16 v[62:65], v[158:161], v[190:193], v[62:65]
	v_mfma_f32_16x16x32_bf16 v[58:61], v[166:169], v[190:193], v[58:61]
	v_mfma_f32_16x16x32_bf16 v[46:49], v[158:161], v[198:201], v[46:49]
	v_mfma_f32_16x16x32_bf16 v[42:45], v[166:169], v[198:201], v[42:45]
	v_mfma_f32_16x16x32_bf16 v[30:33], v[158:161], v[206:209], v[30:33]
	v_mfma_f32_16x16x32_bf16 v[26:29], v[166:169], v[206:209], v[26:29]
	v_mfma_f32_16x16x32_bf16 v[14:17], v[158:161], v[214:217], v[14:17]
	v_mfma_f32_16x16x32_bf16 v[10:13], v[166:169], v[214:217], v[10:13]
	v_mfma_f32_16x16x32_bf16 v[54:57], v[170:173], v[186:189], v[54:57]
	v_mfma_f32_16x16x32_bf16 v[50:53], v[178:181], v[186:189], v[50:53]
	v_mfma_f32_16x16x32_bf16 v[38:41], v[170:173], v[194:197], v[38:41]
	v_mfma_f32_16x16x32_bf16 v[34:37], v[178:181], v[194:197], v[34:37]
	v_mfma_f32_16x16x32_bf16 v[22:25], v[170:173], v[202:205], v[22:25]
	v_mfma_f32_16x16x32_bf16 v[18:21], v[178:181], v[202:205], v[18:21]
	v_mfma_f32_16x16x32_bf16 v[6:9], v[170:173], v[210:213], v[6:9]
	v_mfma_f32_16x16x32_bf16 v[2:5], v[178:181], v[210:213], v[2:5]
	v_mfma_f32_16x16x32_bf16 v[54:57], v[174:177], v[190:193], v[54:57]
	v_mfma_f32_16x16x32_bf16 v[50:53], v[182:185], v[190:193], v[50:53]
	v_mfma_f32_16x16x32_bf16 v[38:41], v[174:177], v[198:201], v[38:41]
	v_mfma_f32_16x16x32_bf16 v[34:37], v[182:185], v[198:201], v[34:37]
	v_mfma_f32_16x16x32_bf16 v[22:25], v[174:177], v[206:209], v[22:25]
	v_mfma_f32_16x16x32_bf16 v[18:21], v[182:185], v[206:209], v[18:21]
	v_mfma_f32_16x16x32_bf16 v[6:9], v[174:177], v[214:217], v[6:9]
	v_mfma_f32_16x16x32_bf16 v[2:5], v[182:185], v[214:217], v[2:5]
	s_barrier
	s_add_i32 s62, 0, 0x18000
	v_add_u32_e32 v157, s62, v152
	s_add_i32 s63, 0, 0x1c000
	ds_read_b128 v[146:149], v157
	ds_read_b128 v[158:161], v157 offset:1024
	ds_read_b128 v[162:165], v157 offset:2048
	ds_read_b128 v[166:169], v157 offset:3072
	v_add_u32_e32 v157, s63, v152
	ds_read_b128 v[170:173], v157
	ds_read_b128 v[174:177], v157 offset:1024
	ds_read_b128 v[178:181], v157 offset:2048
	ds_read_b128 v[182:185], v157 offset:3072
	s_add_u32 s42, s42, 0x40000
	s_addc_u32 s43, s43, 0
	s_mov_b32 m0, s44
	v_lshl_add_u64 v[224:225], s[42:43], 0, v[130:131]
	ds_read_b128 v[186:189], v156 offset:32768
	ds_read_b128 v[190:193], v156 offset:33792
	ds_read_b128 v[194:197], v156 offset:34816
	ds_read_b128 v[198:201], v156 offset:35840
	ds_read_b128 v[202:205], v156 offset:36864
	ds_read_b128 v[206:209], v156 offset:37888
	ds_read_b128 v[210:213], v156 offset:38912
	ds_read_b128 v[214:217], v156 offset:39936
	global_load_lds_dwordx4 v[224:225], off
	v_lshl_add_u64 v[224:225], s[42:43], 0, v[134:135]
	s_mov_b32 m0, s45
	s_nop 0
	global_load_lds_dwordx4 v[224:225], off
	s_waitcnt vmcnt(8)
	s_waitcnt lgkmcnt(0)
	s_barrier
	s_waitcnt lgkmcnt(0)
	v_mfma_f32_16x16x32_bf16 v[126:129], v[146:149], v[186:189], v[126:129]
	v_mfma_f32_16x16x32_bf16 v[122:125], v[162:165], v[186:189], v[122:125]
	v_mfma_f32_16x16x32_bf16 v[110:113], v[146:149], v[194:197], v[110:113]
	v_mfma_f32_16x16x32_bf16 v[106:109], v[162:165], v[194:197], v[106:109]
	v_mfma_f32_16x16x32_bf16 v[94:97], v[146:149], v[202:205], v[94:97]
	v_mfma_f32_16x16x32_bf16 v[90:93], v[162:165], v[202:205], v[90:93]
	v_mfma_f32_16x16x32_bf16 v[78:81], v[146:149], v[210:213], v[78:81]
	v_mfma_f32_16x16x32_bf16 v[74:77], v[162:165], v[210:213], v[74:77]
	v_mfma_f32_16x16x32_bf16 v[126:129], v[158:161], v[190:193], v[126:129]
	v_mfma_f32_16x16x32_bf16 v[122:125], v[166:169], v[190:193], v[122:125]
	v_mfma_f32_16x16x32_bf16 v[110:113], v[158:161], v[198:201], v[110:113]
	v_mfma_f32_16x16x32_bf16 v[106:109], v[166:169], v[198:201], v[106:109]
	v_mfma_f32_16x16x32_bf16 v[94:97], v[158:161], v[206:209], v[94:97]
	v_mfma_f32_16x16x32_bf16 v[90:93], v[166:169], v[206:209], v[90:93]
	v_mfma_f32_16x16x32_bf16 v[78:81], v[158:161], v[214:217], v[78:81]
	v_mfma_f32_16x16x32_bf16 v[74:77], v[166:169], v[214:217], v[74:77]
	v_mfma_f32_16x16x32_bf16 v[118:121], v[170:173], v[186:189], v[118:121]
	v_mfma_f32_16x16x32_bf16 v[114:117], v[178:181], v[186:189], v[114:117]
	v_mfma_f32_16x16x32_bf16 v[102:105], v[170:173], v[194:197], v[102:105]
	v_mfma_f32_16x16x32_bf16 v[98:101], v[178:181], v[194:197], v[98:101]
	v_mfma_f32_16x16x32_bf16 v[86:89], v[170:173], v[202:205], v[86:89]
	v_mfma_f32_16x16x32_bf16 v[82:85], v[178:181], v[202:205], v[82:85]
	v_mfma_f32_16x16x32_bf16 v[70:73], v[170:173], v[210:213], v[70:73]
	v_mfma_f32_16x16x32_bf16 v[66:69], v[178:181], v[210:213], v[66:69]
	v_mfma_f32_16x16x32_bf16 v[118:121], v[174:177], v[190:193], v[118:121]
	v_mfma_f32_16x16x32_bf16 v[114:117], v[182:185], v[190:193], v[114:117]
	v_mfma_f32_16x16x32_bf16 v[102:105], v[174:177], v[198:201], v[102:105]
	v_mfma_f32_16x16x32_bf16 v[98:101], v[182:185], v[198:201], v[98:101]
	v_mfma_f32_16x16x32_bf16 v[86:89], v[174:177], v[206:209], v[86:89]
	v_mfma_f32_16x16x32_bf16 v[82:85], v[182:185], v[206:209], v[82:85]
	v_mfma_f32_16x16x32_bf16 v[70:73], v[174:177], v[214:217], v[70:73]
	v_mfma_f32_16x16x32_bf16 v[66:69], v[182:185], v[214:217], v[66:69]
	s_barrier
; #define PG8_STAGE(bufoff, gbase, voff) do { _Pragma("unroll") for (int _i = 0; _i < 2; ++_i) \
;         __builtin_amdgcn_global_load_lds((const unsigned*)((const char*)(gbase) + (voff)[_i]), (PG8_LAS unsigned*)(lds + (bufoff) + ldsw + _i * 8192), 16, 0, 0); } while (0)
; #define PG8_LDA(dst, b, h) do { _Pragma("unroll") for (int m = 0; m < 4; ++m) _Pragma("unroll") for (int k = 0; k < 2; ++k) dst[m][k] = *(const PG8_LAS bf16x8*)(lds + PG8_SA(b, h) + aoff + m * 2048 + k * 1024); } while (0)
; #define PG8_MMA(ai, bj, At, Bt) do { __builtin_amdgcn_s_setprio(1); _Pragma("unroll") for (int m = 0; m < 4; ++m) _Pragma("unroll") for (int n = 0; n < 2; ++n) _Pragma("unroll") for (int k = 0; k < 2; ++k) \
;         acc[ai][bj][m][n] = __builtin_amdgcn_mfma_f32_16x16x32_bf16(Bt[n][k], At[m][k], acc[ai][bj][m][n], 0, 0, 0); __builtin_amdgcn_s_setprio(0); } while (0)
; #define PG8_WAIT_V(n) asm volatile("s_waitcnt vmcnt(" #n ")" ::: "memory")
; #define PG8_WAIT_L(n) asm volatile("s_waitcnt lgkmcnt(" #n ")" ::: "memory")
; #define PG8_BAR __builtin_amdgcn_s_barrier()
; #define PG8_SCHED __builtin_amdgcn_sched_barrier(0)
; template <class Epi, class Sched, bool ALIGN_EPI = false, bool SP2 = false>
; __device__ __forceinline__ void gemm_phase(PG8_LAS unsigned char* lds, const Gemm g, const Sched& S, const Epi& E) {
;     ...
;             PG8_LDA(At, 1, 1); PG8_STAGE(PG8_SB(1, 0), b3, voffB); PG8_STAGE(PG8_SB(1, 1), b3 + hstepB, voffB); PG8_STAGE(PG8_SA(1, 0), a3, voffA);
;             PG8_WAIT_V(8); PG8_WAIT_L(0); PG8_BAR; PG8_MMA(1, 0, At, B0); PG8_MMA(1, 1, At, B1); PG8_BAR; PG8_SCHED;
;     ...
;         if constexpr (ALIGN_EPI) { if (wr == 0) PG8_BAR; }
	s_add_i32 s42, s62, s30
	v_lshl_add_u64 v[150:151], v[150:151], 0, s[10:11]
	s_mov_b32 m0, s42
	ds_read_b128 v[186:189], v156 offset:49152
	ds_read_b128 v[190:193], v156 offset:50176
	ds_read_b128 v[194:197], v156 offset:51200
	ds_read_b128 v[198:201], v156 offset:52224
	ds_read_b128 v[202:205], v156 offset:53248
	ds_read_b128 v[206:209], v156 offset:54272
	ds_read_b128 v[210:213], v156 offset:55296
	ds_read_b128 v[214:217], v156 offset:56320
	global_load_lds_dwordx4 v[150:151], off
	s_add_i32 m0, s42, 0x2000
	s_add_u32 s40, s40, 0x10080
	v_lshl_add_u64 v[150:151], v[218:219], 0, s[10:11]
	s_addc_u32 s41, s41, 0
	s_add_i32 s42, s63, s30
	global_load_lds_dwordx4 v[150:151], off
	v_lshl_add_u64 v[150:151], s[40:41], 0, v[132:133]
	s_mov_b32 m0, s42
	s_nop 0
	global_load_lds_dwordx4 v[150:151], off
	v_lshl_add_u64 v[150:151], s[40:41], 0, v[136:137]
	s_add_i32 m0, s42, 0x2000
	s_nop 0
	global_load_lds_dwordx4 v[150:151], off
	v_lshl_add_u64 v[150:151], v[220:221], 0, s[10:11]
	s_mov_b32 m0, s47
	s_nop 0
	global_load_lds_dwordx4 v[150:151], off
	v_lshl_add_u64 v[150:151], v[222:223], 0, s[10:11]
	s_mov_b32 m0, s54
	s_nop 0
	global_load_lds_dwordx4 v[150:151], off
	s_waitcnt vmcnt(8)
	s_waitcnt lgkmcnt(0)
	s_barrier
	s_waitcnt lgkmcnt(0)
	v_mfma_f32_16x16x32_bf16 v[62:65], v[146:149], v[186:189], v[62:65]
	v_mfma_f32_16x16x32_bf16 v[58:61], v[162:165], v[186:189], v[58:61]
	v_mfma_f32_16x16x32_bf16 v[46:49], v[146:149], v[194:197], v[46:49]
	v_mfma_f32_16x16x32_bf16 v[42:45], v[162:165], v[194:197], v[42:45]
	v_mfma_f32_16x16x32_bf16 v[30:33], v[146:149], v[202:205], v[30:33]
	v_mfma_f32_16x16x32_bf16 v[26:29], v[162:165], v[202:205], v[26:29]
	v_mfma_f32_16x16x32_bf16 v[14:17], v[146:149], v[210:213], v[14:17]
	v_mfma_f32_16x16x32_bf16 v[10:13], v[162:165], v[210:213], v[10:13]
	v_mfma_f32_16x16x32_bf16 v[62:65], v[158:161], v[190:193], v[62:65]
	v_mfma_f32_16x16x32_bf16 v[58:61], v[166:169], v[190:193], v[58:61]
	v_mfma_f32_16x16x32_bf16 v[46:49], v[158:161], v[198:201], v[46:49]
	v_mfma_f32_16x16x32_bf16 v[42:45], v[166:169], v[198:201], v[42:45]
	v_mfma_f32_16x16x32_bf16 v[30:33], v[158:161], v[206:209], v[30:33]
	v_mfma_f32_16x16x32_bf16 v[26:29], v[166:169], v[206:209], v[26:29]
	v_mfma_f32_16x16x32_bf16 v[14:17], v[158:161], v[214:217], v[14:17]
	v_mfma_f32_16x16x32_bf16 v[10:13], v[166:169], v[214:217], v[10:13]
	v_mfma_f32_16x16x32_bf16 v[54:57], v[170:173], v[186:189], v[54:57]
	v_mfma_f32_16x16x32_bf16 v[50:53], v[178:181], v[186:189], v[50:53]
	v_mfma_f32_16x16x32_bf16 v[38:41], v[170:173], v[194:197], v[38:41]
	v_mfma_f32_16x16x32_bf16 v[34:37], v[178:181], v[194:197], v[34:37]
	v_mfma_f32_16x16x32_bf16 v[22:25], v[170:173], v[202:205], v[22:25]
	v_mfma_f32_16x16x32_bf16 v[18:21], v[178:181], v[202:205], v[18:21]
	v_mfma_f32_16x16x32_bf16 v[6:9], v[170:173], v[210:213], v[6:9]
	v_mfma_f32_16x16x32_bf16 v[2:5], v[178:181], v[210:213], v[2:5]
	v_mfma_f32_16x16x32_bf16 v[54:57], v[174:177], v[190:193], v[54:57]
	v_mfma_f32_16x16x32_bf16 v[50:53], v[182:185], v[190:193], v[50:53]
	v_mfma_f32_16x16x32_bf16 v[38:41], v[174:177], v[198:201], v[38:41]
	v_mfma_f32_16x16x32_bf16 v[34:37], v[182:185], v[198:201], v[34:37]
	v_mfma_f32_16x16x32_bf16 v[22:25], v[174:177], v[206:209], v[22:25]
	v_mfma_f32_16x16x32_bf16 v[18:21], v[182:185], v[206:209], v[18:21]
	v_mfma_f32_16x16x32_bf16 v[6:9], v[174:177], v[214:217], v[6:9]
	v_mfma_f32_16x16x32_bf16 v[2:5], v[182:185], v[214:217], v[2:5]
	s_barrier
	s_add_i32 s61, s61, 2
	s_add_u32 s38, s38, 0x100
	s_addc_u32 s39, s39, 0
	s_add_u32 s59, s59, 0x100
	s_addc_u32 s60, s60, 0
	s_cmp_gt_u32 s61, 13
	s_cbranch_scc0 .LBB0_1313
	s_and_b64 vcc, exec, s[14:15]
	s_cbranch_vccz .LBB0_1316
	s_barrier

; #define PG8_STAGE(bufoff, gbase, voff) do { _Pragma("unroll") for (int _i = 0; _i < 2; ++_i) \
;         __builtin_amdgcn_global_load_lds((const unsigned*)((const char*)(gbase) + (voff)[_i]), (PG8_LAS unsigned*)(lds + (bufoff) + ldsw + _i * 8192), 16, 0, 0); } while (0)
; #define PG8_LDA(dst, b, h) do { _Pragma("unroll") for (int m = 0; m < 4; ++m) _Pragma("unroll") for (int k = 0; k < 2; ++k) dst[m][k] = *(const PG8_LAS bf16x8*)(lds + PG8_SA(b, h) + aoff + m * 2048 + k * 1024); } while (0)
; #define PG8_LDB(dst, b, h) do { _Pragma("unroll") for (int n = 0; n < 2; ++n) _Pragma("unroll") for (int k = 0; k < 2; ++k) dst[n][k] = *(const PG8_LAS bf16x8*)(lds + PG8_SB(b, h) + boff + n * 2048 + k * 1024); } while (0)
; #define PG8_MMA(ai, bj, At, Bt) do { __builtin_amdgcn_s_setprio(1); _Pragma("unroll") for (int m = 0; m < 4; ++m) _Pragma("unroll") for (int n = 0; n < 2; ++n) _Pragma("unroll") for (int k = 0; k < 2; ++k) \
;         acc[ai][bj][m][n] = __builtin_amdgcn_mfma_f32_16x16x32_bf16(Bt[n][k], At[m][k], acc[ai][bj][m][n], 0, 0, 0); __builtin_amdgcn_s_setprio(0); } while (0)
; #define PG8_WAIT_V(n) asm volatile("s_waitcnt vmcnt(" #n ")" ::: "memory")
; #define PG8_WAIT_L(n) asm volatile("s_waitcnt lgkmcnt(" #n ")" ::: "memory")
; #define PG8_BAR __builtin_amdgcn_s_barrier()
; #define PG8_SCHED __builtin_amdgcn_sched_barrier(0)
; template <class Epi, class Sched, bool ALIGN_EPI = false, bool SP2 = false>
; __device__ __forceinline__ void gemm_phase(PG8_LAS unsigned char* lds, const Gemm g, const Sched& S, const Epi& E) {
;     ...
;             PG8_LDB(B0, 0, 0); PG8_LDB(B1, 0, 1); PG8_SCHED; PG8_LDA(At, 0, 0); PG8_STAGE(PG8_SA(1, 1), a1 + hstep, voffA);
;             PG8_WAIT_V(8); PG8_WAIT_L(0); PG8_BAR; PG8_MMA(0, 0, At, B0); PG8_MMA(0, 1, At, B1); PG8_BAR; PG8_SCHED;
;             PG8_LDA(At, 0, 1); PG8_STAGE(PG8_SB(0, 0), b2, voffB); PG8_STAGE(PG8_SB(0, 1), b2 + hstepB, voffB); PG8_STAGE(PG8_SA(0, 0), a2, voffA);
.LBB0_1429:
	v_add_u32_e32 v164, s43, v150
	v_add_u32_e32 v180, s44, v150
	s_add_u32 s26, s8, s24
	ds_read_b128 v[152:155], v164
	ds_read_b128 v[156:159], v164 offset:1024
	ds_read_b128 v[160:163], v164 offset:2048
	ds_read_b128 v[164:167], v164 offset:3072
	ds_read_b128 v[168:171], v180
	ds_read_b128 v[172:175], v180 offset:1024
	ds_read_b128 v[176:179], v180 offset:2048
	ds_read_b128 v[180:183], v180 offset:3072
	s_addc_u32 s27, s9, s25
	s_add_u32 s26, s26, 0x100
	s_addc_u32 s27, s27, 0
	s_add_u32 s55, s21, s24
	s_addc_u32 s56, s45, s25
	s_cmpk_eq_i32 s24, 0x1f00
	s_cselect_b32 s29, s17, s27
	s_cselect_b32 s28, s46, s26
	s_cselect_b32 s27, s15, s56
	s_cselect_b32 s26, s47, s55
	v_lshl_add_u64 v[212:213], v[146:147], 0, s[24:25]
	s_add_i32 m0, s35, 0xc000
	ds_read_b128 v[184:187], v151
	ds_read_b128 v[188:191], v151 offset:1024
	ds_read_b128 v[192:195], v151 offset:2048
	ds_read_b128 v[196:199], v151 offset:3072
	ds_read_b128 v[200:203], v151 offset:4096
	ds_read_b128 v[204:207], v151 offset:5120
	ds_read_b128 v[208:211], v151 offset:6144
	ds_read_b128 v[218:221], v151 offset:7168
	global_load_lds_dwordx4 v[212:213], off
	v_lshl_add_u64 v[212:213], v[148:149], 0, s[24:25]
	s_add_i32 m0, s35, 0xe000
	s_nop 0
	global_load_lds_dwordx4 v[212:213], off
	s_waitcnt vmcnt(8)
	s_waitcnt lgkmcnt(0)
	s_barrier
	s_waitcnt lgkmcnt(0)
	v_mfma_f32_16x16x32_bf16 v[126:129], v[152:155], v[184:187], v[126:129]
	v_mfma_f32_16x16x32_bf16 v[122:125], v[160:163], v[184:187], v[122:125]
	v_mfma_f32_16x16x32_bf16 v[110:113], v[152:155], v[192:195], v[110:113]
	v_mfma_f32_16x16x32_bf16 v[106:109], v[160:163], v[192:195], v[106:109]
	v_mfma_f32_16x16x32_bf16 v[94:97], v[152:155], v[200:203], v[94:97]
	v_mfma_f32_16x16x32_bf16 v[90:93], v[160:163], v[200:203], v[90:93]
	v_mfma_f32_16x16x32_bf16 v[78:81], v[152:155], v[208:211], v[78:81]
	v_mfma_f32_16x16x32_bf16 v[74:77], v[160:163], v[208:211], v[74:77]
	v_mfma_f32_16x16x32_bf16 v[126:129], v[156:159], v[188:191], v[126:129]
	v_mfma_f32_16x16x32_bf16 v[122:125], v[164:167], v[188:191], v[122:125]
	v_mfma_f32_16x16x32_bf16 v[110:113], v[156:159], v[196:199], v[110:113]
	v_mfma_f32_16x16x32_bf16 v[106:109], v[164:167], v[196:199], v[106:109]
	v_mfma_f32_16x16x32_bf16 v[94:97], v[156:159], v[204:207], v[94:97]
	v_mfma_f32_16x16x32_bf16 v[90:93], v[164:167], v[204:207], v[90:93]
	v_mfma_f32_16x16x32_bf16 v[78:81], v[156:159], v[218:221], v[78:81]
	v_mfma_f32_16x16x32_bf16 v[74:77], v[164:167], v[218:221], v[74:77]
	v_mfma_f32_16x16x32_bf16 v[118:121], v[168:171], v[184:187], v[118:121]
	v_mfma_f32_16x16x32_bf16 v[114:117], v[176:179], v[184:187], v[114:117]
	v_mfma_f32_16x16x32_bf16 v[102:105], v[168:171], v[192:195], v[102:105]
	v_mfma_f32_16x16x32_bf16 v[98:101], v[176:179], v[192:195], v[98:101]
	v_mfma_f32_16x16x32_bf16 v[86:89], v[168:171], v[200:203], v[86:89]
	v_mfma_f32_16x16x32_bf16 v[82:85], v[176:179], v[200:203], v[82:85]
	v_mfma_f32_16x16x32_bf16 v[70:73], v[168:171], v[208:211], v[70:73]
	v_mfma_f32_16x16x32_bf16 v[66:69], v[176:179], v[208:211], v[66:69]
	v_mfma_f32_16x16x32_bf16 v[118:121], v[172:175], v[188:191], v[118:121]
	v_mfma_f32_16x16x32_bf16 v[114:117], v[180:183], v[188:191], v[114:117]
	v_mfma_f32_16x16x32_bf16 v[102:105], v[172:175], v[196:199], v[102:105]
	v_mfma_f32_16x16x32_bf16 v[98:101], v[180:183], v[196:199], v[98:101]
	v_mfma_f32_16x16x32_bf16 v[86:89], v[172:175], v[204:207], v[86:89]
	v_mfma_f32_16x16x32_bf16 v[82:85], v[180:183], v[204:207], v[82:85]
	v_mfma_f32_16x16x32_bf16 v[70:73], v[172:175], v[218:221], v[70:73]
	v_mfma_f32_16x16x32_bf16 v[66:69], v[180:183], v[218:221], v[66:69]
	s_barrier
	s_add_i32 s55, s43, s34
	v_lshl_add_u64 v[212:213], s[26:27], 0, v[132:133]
	s_mov_b32 m0, s55
	ds_read_b128 v[184:187], v151 offset:16384
	ds_read_b128 v[188:191], v151 offset:17408
	ds_read_b128 v[192:195], v151 offset:18432
	ds_read_b128 v[196:199], v151 offset:19456
	ds_read_b128 v[200:203], v151 offset:20480
	ds_read_b128 v[204:207], v151 offset:21504
	ds_read_b128 v[208:211], v151 offset:22528
	ds_read_b128 v[218:221], v151 offset:23552
	global_load_lds_dwordx4 v[212:213], off
	s_add_i32 m0, s55, 0x2000
	s_add_u32 s56, s26, 0x40000
	v_lshl_add_u64 v[222:223], s[26:27], 0, v[136:137]
	s_addc_u32 s57, s27, 0
	s_add_i32 s55, s44, s34
	global_load_lds_dwordx4 v[222:223], off
	v_lshl_add_u64 v[224:225], s[56:57], 0, v[132:133]
	s_mov_b32 m0, s55
	v_lshl_add_u64 v[226:227], s[28:29], 0, v[134:135]
	global_load_lds_dwordx4 v[224:225], off
	v_lshl_add_u64 v[224:225], s[56:57], 0, v[136:137]
	s_add_i32 m0, s55, 0x2000
	s_nop 0
	global_load_lds_dwordx4 v[224:225], off
	v_lshl_add_u64 v[224:225], s[28:29], 0, v[130:131]
	s_mov_b32 m0, s35
	s_nop 0
	global_load_lds_dwordx4 v[224:225], off
	s_mov_b32 m0, s36
	s_nop 0
	global_load_lds_dwordx4 v[226:227], off
	s_waitcnt vmcnt(8)
	s_waitcnt lgkmcnt(0)
	s_barrier
; #define PG8_STAGE(bufoff, gbase, voff) do { _Pragma("unroll") for (int _i = 0; _i < 2; ++_i) \
;         __builtin_amdgcn_global_load_lds((const unsigned*)((const char*)(gbase) + (voff)[_i]), (PG8_LAS unsigned*)(lds + (bufoff) + ldsw + _i * 8192), 16, 0, 0); } while (0)
; #define PG8_LDA(dst, b, h) do { _Pragma("unroll") for (int m = 0; m < 4; ++m) _Pragma("unroll") for (int k = 0; k < 2; ++k) dst[m][k] = *(const PG8_LAS bf16x8*)(lds + PG8_SA(b, h) + aoff + m * 2048 + k * 1024); } while (0)
; #define PG8_LDB(dst, b, h) do { _Pragma("unroll") for (int n = 0; n < 2; ++n) _Pragma("unroll") for (int k = 0; k < 2; ++k) dst[n][k] = *(const PG8_LAS bf16x8*)(lds + PG8_SB(b, h) + boff + n * 2048 + k * 1024); } while (0)
; #define PG8_MMA(ai, bj, At, Bt) do { __builtin_amdgcn_s_setprio(1); _Pragma("unroll") for (int m = 0; m < 4; ++m) _Pragma("unroll") for (int n = 0; n < 2; ++n) _Pragma("unroll") for (int k = 0; k < 2; ++k) \
;         acc[ai][bj][m][n] = __builtin_amdgcn_mfma_f32_16x16x32_bf16(Bt[n][k], At[m][k], acc[ai][bj][m][n], 0, 0, 0); __builtin_amdgcn_s_setprio(0); } while (0)
; #define PG8_WAIT_V(n) asm volatile("s_waitcnt vmcnt(" #n ")" ::: "memory")
; #define PG8_WAIT_L(n) asm volatile("s_waitcnt lgkmcnt(" #n ")" ::: "memory")
; #define PG8_BAR __builtin_amdgcn_s_barrier()
; #define PG8_SCHED __builtin_amdgcn_sched_barrier(0)
; template <class Epi, class Sched, bool ALIGN_EPI = false, bool SP2 = false>
; __device__ __forceinline__ void gemm_phase(PG8_LAS unsigned char* lds, const Gemm g, const Sched& S, const Epi& E) {
;     ...
;             PG8_WAIT_V(8); PG8_WAIT_L(0); PG8_BAR; PG8_MMA(1, 0, At, B0); PG8_MMA(1, 1, At, B1); PG8_BAR; PG8_SCHED;
;             PG8_LDB(B0, 1, 0); PG8_LDB(B1, 1, 1); PG8_SCHED; PG8_LDA(At, 1, 0); PG8_STAGE(PG8_SA(0, 1), a2 + hstep, voffA);
;             PG8_WAIT_V(8); PG8_WAIT_L(0); PG8_BAR; PG8_MMA(0, 0, At, B0); PG8_MMA(0, 1, At, B1); PG8_BAR; PG8_SCHED;
	s_waitcnt lgkmcnt(0)
	v_mfma_f32_16x16x32_bf16 v[62:65], v[152:155], v[184:187], v[62:65]
	v_mfma_f32_16x16x32_bf16 v[58:61], v[160:163], v[184:187], v[58:61]
	v_mfma_f32_16x16x32_bf16 v[46:49], v[152:155], v[192:195], v[46:49]
	v_mfma_f32_16x16x32_bf16 v[42:45], v[160:163], v[192:195], v[42:45]
	v_mfma_f32_16x16x32_bf16 v[30:33], v[152:155], v[200:203], v[30:33]
	v_mfma_f32_16x16x32_bf16 v[26:29], v[160:163], v[200:203], v[26:29]
	v_mfma_f32_16x16x32_bf16 v[14:17], v[152:155], v[208:211], v[14:17]
	v_mfma_f32_16x16x32_bf16 v[10:13], v[160:163], v[208:211], v[10:13]
	v_mfma_f32_16x16x32_bf16 v[62:65], v[156:159], v[188:191], v[62:65]
	v_mfma_f32_16x16x32_bf16 v[58:61], v[164:167], v[188:191], v[58:61]
	v_mfma_f32_16x16x32_bf16 v[46:49], v[156:159], v[196:199], v[46:49]
	v_mfma_f32_16x16x32_bf16 v[42:45], v[164:167], v[196:199], v[42:45]
	v_mfma_f32_16x16x32_bf16 v[30:33], v[156:159], v[204:207], v[30:33]
	v_mfma_f32_16x16x32_bf16 v[26:29], v[164:167], v[204:207], v[26:29]
	v_mfma_f32_16x16x32_bf16 v[14:17], v[156:159], v[218:221], v[14:17]
	v_mfma_f32_16x16x32_bf16 v[10:13], v[164:167], v[218:221], v[10:13]
	v_mfma_f32_16x16x32_bf16 v[54:57], v[168:171], v[184:187], v[54:57]
	v_mfma_f32_16x16x32_bf16 v[50:53], v[176:179], v[184:187], v[50:53]
	v_mfma_f32_16x16x32_bf16 v[38:41], v[168:171], v[192:195], v[38:41]
	v_mfma_f32_16x16x32_bf16 v[34:37], v[176:179], v[192:195], v[34:37]
	v_mfma_f32_16x16x32_bf16 v[22:25], v[168:171], v[200:203], v[22:25]
	v_mfma_f32_16x16x32_bf16 v[18:21], v[176:179], v[200:203], v[18:21]
	v_mfma_f32_16x16x32_bf16 v[6:9], v[168:171], v[208:211], v[6:9]
	v_mfma_f32_16x16x32_bf16 v[2:5], v[176:179], v[208:211], v[2:5]
	v_mfma_f32_16x16x32_bf16 v[54:57], v[172:175], v[188:191], v[54:57]
	v_mfma_f32_16x16x32_bf16 v[50:53], v[180:183], v[188:191], v[50:53]
	v_mfma_f32_16x16x32_bf16 v[38:41], v[172:175], v[196:199], v[38:41]
	v_mfma_f32_16x16x32_bf16 v[34:37], v[180:183], v[196:199], v[34:37]
	v_mfma_f32_16x16x32_bf16 v[22:25], v[172:175], v[204:207], v[22:25]
	v_mfma_f32_16x16x32_bf16 v[18:21], v[180:183], v[204:207], v[18:21]
	v_mfma_f32_16x16x32_bf16 v[6:9], v[172:175], v[218:221], v[6:9]
	v_mfma_f32_16x16x32_bf16 v[2:5], v[180:183], v[218:221], v[2:5]
	s_barrier
	s_add_i32 s55, 0, 0x18000
	s_add_i32 s56, 0, 0x1c000
	v_add_u32_e32 v164, s55, v150
	v_add_u32_e32 v180, s56, v150
	ds_read_b128 v[152:155], v164
	ds_read_b128 v[156:159], v164 offset:1024
	ds_read_b128 v[160:163], v164 offset:2048
	ds_read_b128 v[164:167], v164 offset:3072
	ds_read_b128 v[168:171], v180
	ds_read_b128 v[172:175], v180 offset:1024
	ds_read_b128 v[176:179], v180 offset:2048
	ds_read_b128 v[180:183], v180 offset:3072
	s_add_u32 s28, s28, 0x100000
	s_addc_u32 s29, s29, 0
	s_mov_b32 m0, s37
	v_lshl_add_u64 v[228:229], s[28:29], 0, v[130:131]
	ds_read_b128 v[184:187], v151 offset:32768
	ds_read_b128 v[188:191], v151 offset:33792
	ds_read_b128 v[192:195], v151 offset:34816
	ds_read_b128 v[196:199], v151 offset:35840
	ds_read_b128 v[200:203], v151 offset:36864
	ds_read_b128 v[204:207], v151 offset:37888
	ds_read_b128 v[208:211], v151 offset:38912
	ds_read_b128 v[218:221], v151 offset:39936
	global_load_lds_dwordx4 v[228:229], off
	v_lshl_add_u64 v[228:229], s[28:29], 0, v[134:135]
	s_mov_b32 m0, s39
	s_nop 0
	global_load_lds_dwordx4 v[228:229], off
	s_waitcnt vmcnt(8)
	s_waitcnt lgkmcnt(0)
	s_barrier
	s_waitcnt lgkmcnt(0)
	v_mfma_f32_16x16x32_bf16 v[126:129], v[152:155], v[184:187], v[126:129]
	v_mfma_f32_16x16x32_bf16 v[122:125], v[160:163], v[184:187], v[122:125]
	v_mfma_f32_16x16x32_bf16 v[110:113], v[152:155], v[192:195], v[110:113]
	v_mfma_f32_16x16x32_bf16 v[106:109], v[160:163], v[192:195], v[106:109]
	v_mfma_f32_16x16x32_bf16 v[94:97], v[152:155], v[200:203], v[94:97]
	v_mfma_f32_16x16x32_bf16 v[90:93], v[160:163], v[200:203], v[90:93]
	v_mfma_f32_16x16x32_bf16 v[78:81], v[152:155], v[208:211], v[78:81]
	v_mfma_f32_16x16x32_bf16 v[74:77], v[160:163], v[208:211], v[74:77]
	v_mfma_f32_16x16x32_bf16 v[126:129], v[156:159], v[188:191], v[126:129]
	v_mfma_f32_16x16x32_bf16 v[122:125], v[164:167], v[188:191], v[122:125]
	v_mfma_f32_16x16x32_bf16 v[110:113], v[156:159], v[196:199], v[110:113]
	v_mfma_f32_16x16x32_bf16 v[106:109], v[164:167], v[196:199], v[106:109]
	v_mfma_f32_16x16x32_bf16 v[94:97], v[156:159], v[204:207], v[94:97]
	v_mfma_f32_16x16x32_bf16 v[90:93], v[164:167], v[204:207], v[90:93]
	v_mfma_f32_16x16x32_bf16 v[78:81], v[156:159], v[218:221], v[78:81]
	v_mfma_f32_16x16x32_bf16 v[74:77], v[164:167], v[218:221], v[74:77]
	v_mfma_f32_16x16x32_bf16 v[118:121], v[168:171], v[184:187], v[118:121]
	v_mfma_f32_16x16x32_bf16 v[114:117], v[176:179], v[184:187], v[114:117]
	v_mfma_f32_16x16x32_bf16 v[102:105], v[168:171], v[192:195], v[102:105]
	v_mfma_f32_16x16x32_bf16 v[98:101], v[176:179], v[192:195], v[98:101]
	v_mfma_f32_16x16x32_bf16 v[86:89], v[168:171], v[200:203], v[86:89]
	v_mfma_f32_16x16x32_bf16 v[82:85], v[176:179], v[200:203], v[82:85]
	v_mfma_f32_16x16x32_bf16 v[70:73], v[168:171], v[208:211], v[70:73]
	v_mfma_f32_16x16x32_bf16 v[66:69], v[176:179], v[208:211], v[66:69]
	v_mfma_f32_16x16x32_bf16 v[118:121], v[172:175], v[188:191], v[118:121]
	v_mfma_f32_16x16x32_bf16 v[114:117], v[180:183], v[188:191], v[114:117]
	v_mfma_f32_16x16x32_bf16 v[102:105], v[172:175], v[196:199], v[102:105]
	v_mfma_f32_16x16x32_bf16 v[98:101], v[180:183], v[196:199], v[98:101]
	v_mfma_f32_16x16x32_bf16 v[86:89], v[172:175], v[204:207], v[86:89]
	v_mfma_f32_16x16x32_bf16 v[82:85], v[180:183], v[204:207], v[82:85]
	v_mfma_f32_16x16x32_bf16 v[70:73], v[172:175], v[218:221], v[70:73]
	v_mfma_f32_16x16x32_bf16 v[66:69], v[180:183], v[218:221], v[66:69]
	s_barrier
; #define PG8_STAGE(bufoff, gbase, voff) do { _Pragma("unroll") for (int _i = 0; _i < 2; ++_i) \
;         __builtin_amdgcn_global_load_lds((const unsigned*)((const char*)(gbase) + (voff)[_i]), (PG8_LAS unsigned*)(lds + (bufoff) + ldsw + _i * 8192), 16, 0, 0); } while (0)
; #define PG8_LDA(dst, b, h) do { _Pragma("unroll") for (int m = 0; m < 4; ++m) _Pragma("unroll") for (int k = 0; k < 2; ++k) dst[m][k] = *(const PG8_LAS bf16x8*)(lds + PG8_SA(b, h) + aoff + m * 2048 + k * 1024); } while (0)
; #define PG8_MMA(ai, bj, At, Bt) do { __builtin_amdgcn_s_setprio(1); _Pragma("unroll") for (int m = 0; m < 4; ++m) _Pragma("unroll") for (int n = 0; n < 2; ++n) _Pragma("unroll") for (int k = 0; k < 2; ++k) \
;         acc[ai][bj][m][n] = __builtin_amdgcn_mfma_f32_16x16x32_bf16(Bt[n][k], At[m][k], acc[ai][bj][m][n], 0, 0, 0); __builtin_amdgcn_s_setprio(0); } while (0)
; #define PG8_WAIT_V(n) asm volatile("s_waitcnt vmcnt(" #n ")" ::: "memory")
; #define PG8_WAIT_L(n) asm volatile("s_waitcnt lgkmcnt(" #n ")" ::: "memory")
; #define PG8_BAR __builtin_amdgcn_s_barrier()
; #define PG8_SCHED __builtin_amdgcn_sched_barrier(0)
; template <class Epi, class Sched, bool ALIGN_EPI = false, bool SP2 = false>
; __device__ __forceinline__ void gemm_phase(PG8_LAS unsigned char* lds, const Gemm g, const Sched& S, const Epi& E) {
;     ...
;             PG8_LDA(At, 1, 1); PG8_STAGE(PG8_SB(1, 0), b3, voffB); PG8_STAGE(PG8_SB(1, 1), b3 + hstepB, voffB); PG8_STAGE(PG8_SA(1, 0), a3, voffA);
;             PG8_WAIT_V(8); PG8_WAIT_L(0); PG8_BAR; PG8_MMA(1, 0, At, B0); PG8_MMA(1, 1, At, B1); PG8_BAR; PG8_SCHED;
;     ...
; #pragma unroll
;         for (int a = 0; a < 2; ++a)
; #pragma unroll
;             for (int b = 0; b < 2; ++b)
; #pragma unroll
;                 for (int m = 0; m < 4; ++m)
; #pragma unroll
;                     for (int n = 0; n < 2; ++n) acc[a][b][m][n] = (f32x4){0.f, 0.f, 0.f, 0.f};
;         cur = nxt; cA = nA; cB = nB; ++ui;
	s_add_i32 s28, s55, s34
	v_lshl_add_u64 v[212:213], v[212:213], 0, s[10:11]
	s_mov_b32 m0, s28
	ds_read_b128 v[184:187], v151 offset:49152
	ds_read_b128 v[188:191], v151 offset:50176
	ds_read_b128 v[192:195], v151 offset:51200
	ds_read_b128 v[196:199], v151 offset:52224
	ds_read_b128 v[200:203], v151 offset:53248
	ds_read_b128 v[204:207], v151 offset:54272
	ds_read_b128 v[208:211], v151 offset:55296
	ds_read_b128 v[218:221], v151 offset:56320
	global_load_lds_dwordx4 v[212:213], off
	s_add_i32 m0, s28, 0x2000
	s_add_u32 s26, s26, 0x40080
	v_lshl_add_u64 v[212:213], v[222:223], 0, s[10:11]
	s_addc_u32 s27, s27, 0
	s_add_i32 s28, s56, s34
	global_load_lds_dwordx4 v[212:213], off
	v_lshl_add_u64 v[212:213], s[26:27], 0, v[132:133]
	s_mov_b32 m0, s28
	s_nop 0
	global_load_lds_dwordx4 v[212:213], off
	v_lshl_add_u64 v[212:213], s[26:27], 0, v[136:137]
	s_add_i32 m0, s28, 0x2000
	s_nop 0
	global_load_lds_dwordx4 v[212:213], off
	v_lshl_add_u64 v[212:213], v[224:225], 0, s[10:11]
	s_mov_b32 m0, s40
	s_nop 0
	global_load_lds_dwordx4 v[212:213], off
	v_lshl_add_u64 v[212:213], v[226:227], 0, s[10:11]
	s_mov_b32 m0, s41
	s_nop 0
	global_load_lds_dwordx4 v[212:213], off
	s_waitcnt vmcnt(8)
	s_waitcnt lgkmcnt(0)
	s_barrier
	s_waitcnt lgkmcnt(0)
	v_mfma_f32_16x16x32_bf16 v[62:65], v[152:155], v[184:187], v[62:65]
	v_mfma_f32_16x16x32_bf16 v[58:61], v[160:163], v[184:187], v[58:61]
	v_mfma_f32_16x16x32_bf16 v[46:49], v[152:155], v[192:195], v[46:49]
	v_mfma_f32_16x16x32_bf16 v[42:45], v[160:163], v[192:195], v[42:45]
	v_mfma_f32_16x16x32_bf16 v[30:33], v[152:155], v[200:203], v[30:33]
	v_mfma_f32_16x16x32_bf16 v[26:29], v[160:163], v[200:203], v[26:29]
	v_mfma_f32_16x16x32_bf16 v[14:17], v[152:155], v[208:211], v[14:17]
	v_mfma_f32_16x16x32_bf16 v[10:13], v[160:163], v[208:211], v[10:13]
	v_mfma_f32_16x16x32_bf16 v[62:65], v[156:159], v[188:191], v[62:65]
	v_mfma_f32_16x16x32_bf16 v[58:61], v[164:167], v[188:191], v[58:61]
	v_mfma_f32_16x16x32_bf16 v[46:49], v[156:159], v[196:199], v[46:49]
	v_mfma_f32_16x16x32_bf16 v[42:45], v[164:167], v[196:199], v[42:45]
	v_mfma_f32_16x16x32_bf16 v[30:33], v[156:159], v[204:207], v[30:33]
	v_mfma_f32_16x16x32_bf16 v[26:29], v[164:167], v[204:207], v[26:29]
	v_mfma_f32_16x16x32_bf16 v[14:17], v[156:159], v[218:221], v[14:17]
	v_mfma_f32_16x16x32_bf16 v[10:13], v[164:167], v[218:221], v[10:13]
	v_mfma_f32_16x16x32_bf16 v[54:57], v[168:171], v[184:187], v[54:57]
	v_mfma_f32_16x16x32_bf16 v[50:53], v[176:179], v[184:187], v[50:53]
	v_mfma_f32_16x16x32_bf16 v[38:41], v[168:171], v[192:195], v[38:41]
	v_mfma_f32_16x16x32_bf16 v[34:37], v[176:179], v[192:195], v[34:37]
	v_mfma_f32_16x16x32_bf16 v[22:25], v[168:171], v[200:203], v[22:25]
	v_mfma_f32_16x16x32_bf16 v[18:21], v[176:179], v[200:203], v[18:21]
	v_mfma_f32_16x16x32_bf16 v[6:9], v[168:171], v[208:211], v[6:9]
	v_mfma_f32_16x16x32_bf16 v[2:5], v[176:179], v[208:211], v[2:5]
	v_mfma_f32_16x16x32_bf16 v[54:57], v[172:175], v[188:191], v[54:57]
	v_mfma_f32_16x16x32_bf16 v[50:53], v[180:183], v[188:191], v[50:53]
	v_mfma_f32_16x16x32_bf16 v[38:41], v[172:175], v[196:199], v[38:41]
	v_mfma_f32_16x16x32_bf16 v[34:37], v[180:183], v[196:199], v[34:37]
	v_mfma_f32_16x16x32_bf16 v[22:25], v[172:175], v[204:207], v[22:25]
	v_mfma_f32_16x16x32_bf16 v[18:21], v[180:183], v[204:207], v[18:21]
	v_mfma_f32_16x16x32_bf16 v[6:9], v[172:175], v[218:221], v[6:9]
	v_mfma_f32_16x16x32_bf16 v[2:5], v[180:183], v[218:221], v[2:5]
	s_barrier
	s_add_i32 s54, s54, 2
	s_add_u32 s24, s24, 0x100
	s_addc_u32 s25, s25, 0
	s_cmp_gt_u32 s54, 61
	s_cbranch_scc0 .LBB0_1429
	s_add_u32 s24, s21, 0xffffff00
	s_addc_u32 s25, s45, -1
	s_andn2_b64 vcc, exec, s[2:3]
	s_cbranch_vccnz .LBB0_1420
	v_mov_b32_e32 v2, 0
	s_mov_b32 s6, s14
	s_mov_b32 s4, s16
	s_mov_b64 s[8:9], s[22:23]
	s_mov_b32 s42, s20
	v_mov_b32_e32 v3, v2
	v_mov_b32_e32 v4, v2
	v_mov_b32_e32 v5, v2
	v_mov_b32_e32 v6, v2
	v_mov_b32_e32 v7, v2
	v_mov_b32_e32 v8, v2
	v_mov_b32_e32 v9, v2
	v_mov_b32_e32 v18, v2
	v_mov_b32_e32 v19, v2
	v_mov_b32_e32 v20, v2
	v_mov_b32_e32 v21, v2
	v_mov_b32_e32 v22, v2
	v_mov_b32_e32 v23, v2
	v_mov_b32_e32 v24, v2
	v_mov_b32_e32 v25, v2
	v_mov_b32_e32 v34, v2
	v_mov_b32_e32 v35, v2
	v_mov_b32_e32 v36, v2
	v_mov_b32_e32 v37, v2
	v_mov_b32_e32 v38, v2
	v_mov_b32_e32 v39, v2
	v_mov_b32_e32 v40, v2
	v_mov_b32_e32 v41, v2
	v_mov_b32_e32 v50, v2
	v_mov_b32_e32 v51, v2
	v_mov_b32_e32 v52, v2
	v_mov_b32_e32 v53, v2
	v_mov_b32_e32 v54, v2
	v_mov_b32_e32 v55, v2
	v_mov_b32_e32 v56, v2
	v_mov_b32_e32 v57, v2
	v_mov_b32_e32 v10, v2
	v_mov_b32_e32 v11, v2
	v_mov_b32_e32 v12, v2
	v_mov_b32_e32 v13, v2
	v_mov_b32_e32 v14, v2
	v_mov_b32_e32 v15, v2
	v_mov_b32_e32 v16, v2
	v_mov_b32_e32 v17, v2
	v_mov_b32_e32 v26, v2
	v_mov_b32_e32 v27, v2
	v_mov_b32_e32 v28, v2
	v_mov_b32_e32 v29, v2
	v_mov_b32_e32 v30, v2
	v_mov_b32_e32 v31, v2
	v_mov_b32_e32 v32, v2
	v_mov_b32_e32 v33, v2
	v_mov_b32_e32 v42, v2
	v_mov_b32_e32 v43, v2
	v_mov_b32_e32 v44, v2
	v_mov_b32_e32 v45, v2
	v_mov_b32_e32 v46, v2
	v_mov_b32_e32 v47, v2
	v_mov_b32_e32 v48, v2
	v_mov_b32_e32 v49, v2
	v_mov_b32_e32 v58, v2
	v_mov_b32_e32 v59, v2
	v_mov_b32_e32 v60, v2
	v_mov_b32_e32 v61, v2
	v_mov_b32_e32 v62, v2
	v_mov_b32_e32 v63, v2
	v_mov_b32_e32 v64, v2
	v_mov_b32_e32 v65, v2
	v_mov_b32_e32 v66, v2
	v_mov_b32_e32 v67, v2
	v_mov_b32_e32 v68, v2
	v_mov_b32_e32 v69, v2
	v_mov_b32_e32 v70, v2
	v_mov_b32_e32 v71, v2
	v_mov_b32_e32 v72, v2
	v_mov_b32_e32 v73, v2
	v_mov_b32_e32 v82, v2
	v_mov_b32_e32 v83, v2
	v_mov_b32_e32 v84, v2
	v_mov_b32_e32 v85, v2
	v_mov_b32_e32 v86, v2
	v_mov_b32_e32 v87, v2
	v_mov_b32_e32 v88, v2
	v_mov_b32_e32 v89, v2
	v_mov_b32_e32 v98, v2
	v_mov_b32_e32 v99, v2
	v_mov_b32_e32 v100, v2
	v_mov_b32_e32 v101, v2
	v_mov_b32_e32 v102, v2
	v_mov_b32_e32 v103, v2
	v_mov_b32_e32 v104, v2
	v_mov_b32_e32 v105, v2
	v_mov_b32_e32 v114, v2
	v_mov_b32_e32 v115, v2
	v_mov_b32_e32 v116, v2
	v_mov_b32_e32 v117, v2
	v_mov_b32_e32 v118, v2
	v_mov_b32_e32 v119, v2
	v_mov_b32_e32 v120, v2
	v_mov_b32_e32 v121, v2
	v_mov_b32_e32 v74, v2
	v_mov_b32_e32 v75, v2
	v_mov_b32_e32 v76, v2
	v_mov_b32_e32 v77, v2
	v_mov_b32_e32 v78, v2
	v_mov_b32_e32 v79, v2
	v_mov_b32_e32 v80, v2
	v_mov_b32_e32 v81, v2
	v_mov_b32_e32 v90, v2
	v_mov_b32_e32 v91, v2
	v_mov_b32_e32 v92, v2
	v_mov_b32_e32 v93, v2
	v_mov_b32_e32 v94, v2
	v_mov_b32_e32 v95, v2
	v_mov_b32_e32 v96, v2
	v_mov_b32_e32 v97, v2
	v_mov_b32_e32 v106, v2
	v_mov_b32_e32 v107, v2
	v_mov_b32_e32 v108, v2
	v_mov_b32_e32 v109, v2
	v_mov_b32_e32 v110, v2
	v_mov_b32_e32 v111, v2
	v_mov_b32_e32 v112, v2
	v_mov_b32_e32 v113, v2
	v_mov_b32_e32 v122, v2
	v_mov_b32_e32 v123, v2
	v_mov_b32_e32 v124, v2
	v_mov_b32_e32 v125, v2
	v_mov_b32_e32 v126, v2
	v_mov_b32_e32 v127, v2
	v_mov_b32_e32 v128, v2
	v_mov_b32_e32 v129, v2
	s_andn2_b64 vcc, exec, s[0:1]
	s_cbranch_vccnz .LBB0_1421
